# LN1->mlp1 grid barrier replaced by per-row-block completion records (sc1 H/X stores, vmcnt(0), sc1 16-B record; mlp1 tiles poll 8 records of their row block and read operands with sc1 DMA loads)
# speedup vs baseline: 1.0200x; 1.0150x over previous
.LBB0_8:
	s_cmp_le_i32 s18, s80
	s_cbranch_scc1 .LBB0_74
	s_cmp_eq_u32 s18, 5
	s_cbranch_scc1 .LBB0_74
	s_cmp_eq_u32 s18, 10
	s_cbranch_scc1 .LBB0_74
	s_cmp_eq_u32 s18, 15
	s_cbranch_scc1 .LBB0_74
	s_cmp_eq_u32 s18, 20
	s_cbranch_scc1 .LBB0_74
	v_readlane_b32 s0, v253, 19
	v_readlane_b32 s1, v253, 20
	s_andn2_b64 vcc, exec, s[0:1]
	s_cbranch_vccnz .LBB0_21
	s_barrier
	s_mov_b64 s[0:1], exec
	v_readlane_b32 s8, v253, 21
	v_readlane_b32 s9, v253, 22
	s_and_b64 s[8:9], s[0:1], s[8:9]
	s_mov_b64 exec, s[8:9]
	s_cbranch_execz .LBB0_20
	buffer_wbl2 sc1
	s_waitcnt vmcnt(0)
	s_load_dwordx2 s[22:23], s[78:79], 0x58
	s_mov_b64 s[26:27], exec
	v_mbcnt_lo_u32_b32 v2, s26, 0
	v_mbcnt_hi_u32_b32 v2, s27, v2
	v_cmp_eq_u32_e32 vcc, 0, v2
	s_waitcnt lgkmcnt(0)
	global_load_dword v0, v1, s[22:23] offset:40
	s_and_saveexec_b64 s[34:35], vcc
	s_cbranch_execz .LBB0_13
	s_bcnt1_i32_b64 s5, s[26:27]
	v_mov_b32_e32 v3, s5
	global_atomic_add v3, v1, v3, s[22:23] offset:32 sc0

.LBB0_80:
	v_readfirstlane_b32 s6, v137
	s_lshr_b32 s6, s6, 6
	s_and_b32 s14, s6, 1
	s_lshr_b32 s19, s6, 1
	s_lshl_b32 s19, s19, 6
	s_add_i32 s19, s19, s26
	s_lshl_b32 s14, s14, 6
	s_add_i32 s14, s14, s22
	s_lshl_b32 s6, s6, 12
	s_add_i32 s6, s6, 0x18000
	v_and_b32_e32 v202, 63, v137
	v_and_b32_e32 v203, 15, v202
	v_lshrrev_b32_e32 v204, 4, v202
	v_and_b32_e32 v205, 3, v203
	v_lshrrev_b32_e32 v206, 2, v203
	v_lshl_or_b32 v207, v204, 2, v205
	s_mov_b32 s36, 0xaaaaaaaa
	s_mov_b32 s37, 0xaaaaaaaa
	s_mov_b32 s50, 0xcccccccc
	s_mov_b32 s51, 0xcccccccc
	v_and_b32_e32 v208, 7, v207
	v_lshlrev_b32_e32 v208, 1, v208
	v_or_b32_e32 v209, 0, v206
	v_xor_b32_e32 v209, v209, v208
	v_lshlrev_b32_e32 v209, 3, v209
	v_lshl_add_u32 v209, v207, 7, v209
	v_add_u32_e32 v209, s6, v209
	v_or_b32_e32 v210, 4, v206
	v_xor_b32_e32 v210, v210, v208
	v_lshlrev_b32_e32 v210, 3, v210
	v_lshl_add_u32 v210, v207, 7, v210
	v_add_u32_e32 v210, s6, v210
	v_or_b32_e32 v211, 8, v206
	v_xor_b32_e32 v211, v211, v208
	v_lshlrev_b32_e32 v211, 3, v211
	v_lshl_add_u32 v211, v207, 7, v211
	v_add_u32_e32 v211, s6, v211
	v_or_b32_e32 v212, 12, v206
	v_xor_b32_e32 v212, v212, v208
	v_lshlrev_b32_e32 v212, 3, v212
	v_lshl_add_u32 v212, v207, 7, v212
	v_add_u32_e32 v212, s6, v212
	v_lshl_add_u32 v213, v202, 4, s6
	v_lshrrev_b32_e32 v214, 3, v202
	v_and_b32_e32 v215, 7, v202
	v_xor_b32_e32 v215, v215, v214
	v_add_u32_e32 v214, s19, v214
	v_lshlrev_b32_e32 v214, 13, v214
	v_lshl_add_u32 v214, v215, 4, v214
	s_lshl_b32 s27, s14, 1
	v_add_u32_e32 v214, s27, v214
	s_add_u32 s16, s94, 0xe1d8000
	s_addc_u32 s17, s95, 0
	v_max_f32_e32 v62, 0, v62
	v_max_f32_e32 v63, 0, v63
	v_max_f32_e32 v64, 0, v64
	v_max_f32_e32 v65, 0, v65
	v_mul_f32_e32 v62, v62, v62
	v_mul_f32_e32 v63, v63, v63
	v_mul_f32_e32 v64, v64, v64
	v_mul_f32_e32 v65, v65, v65
	v_max_f32_e32 v58, 0, v58
	v_max_f32_e32 v59, 0, v59
	v_max_f32_e32 v60, 0, v60
	v_max_f32_e32 v61, 0, v61
	v_mul_f32_e32 v58, v58, v58
	v_mul_f32_e32 v59, v59, v59
	v_mul_f32_e32 v60, v60, v60
	v_mul_f32_e32 v61, v61, v61
	v_max_f32_e32 v54, 0, v54
	v_max_f32_e32 v55, 0, v55
	v_max_f32_e32 v56, 0, v56
	v_max_f32_e32 v57, 0, v57
	v_mul_f32_e32 v54, v54, v54
	v_mul_f32_e32 v55, v55, v55
	v_mul_f32_e32 v56, v56, v56
	v_mul_f32_e32 v57, v57, v57
	v_max_f32_e32 v50, 0, v50
	v_max_f32_e32 v51, 0, v51
	v_max_f32_e32 v52, 0, v52
	v_max_f32_e32 v53, 0, v53
	v_mul_f32_e32 v50, v50, v50
	v_mul_f32_e32 v51, v51, v51
	v_mul_f32_e32 v52, v52, v52
	v_mul_f32_e32 v53, v53, v53
	v_max_f32_e32 v46, 0, v46
	v_max_f32_e32 v47, 0, v47
	v_max_f32_e32 v48, 0, v48
	v_max_f32_e32 v49, 0, v49
	v_mul_f32_e32 v46, v46, v46
	v_mul_f32_e32 v47, v47, v47
	v_mul_f32_e32 v48, v48, v48
	v_mul_f32_e32 v49, v49, v49
	v_max_f32_e32 v42, 0, v42
	v_max_f32_e32 v43, 0, v43
	v_max_f32_e32 v44, 0, v44
	v_max_f32_e32 v45, 0, v45
	v_mul_f32_e32 v42, v42, v42
	v_mul_f32_e32 v43, v43, v43
	v_mul_f32_e32 v44, v44, v44
	v_mul_f32_e32 v45, v45, v45
	v_max_f32_e32 v38, 0, v38
	v_max_f32_e32 v39, 0, v39
	v_max_f32_e32 v40, 0, v40
	v_max_f32_e32 v41, 0, v41
	v_mul_f32_e32 v38, v38, v38
	v_mul_f32_e32 v39, v39, v39
	v_mul_f32_e32 v40, v40, v40
	v_mul_f32_e32 v41, v41, v41
	v_max_f32_e32 v34, 0, v34
	v_max_f32_e32 v35, 0, v35
	v_max_f32_e32 v36, 0, v36
	v_max_f32_e32 v37, 0, v37
	v_mul_f32_e32 v34, v34, v34
	v_mul_f32_e32 v35, v35, v35
	v_mul_f32_e32 v36, v36, v36
	v_mul_f32_e32 v37, v37, v37
	s_nop 1
	v_mov_b32_dpp v72, v63 quad_perm:[1,0,3,2] row_mask:0xf bank_mask:0xf
	v_mov_b32_dpp v73, v62 quad_perm:[1,0,3,2] row_mask:0xf bank_mask:0xf
	v_mov_b32_dpp v74, v65 quad_perm:[1,0,3,2] row_mask:0xf bank_mask:0xf
	v_mov_b32_dpp v75, v64 quad_perm:[1,0,3,2] row_mask:0xf bank_mask:0xf
	v_cndmask_b32_e64 v62, v62, v72, s[36:37]
	v_cndmask_b32_e64 v63, v73, v63, s[36:37]
	v_cndmask_b32_e64 v64, v64, v74, s[36:37]
	v_cndmask_b32_e64 v65, v75, v65, s[36:37]
	s_nop 1
	v_mov_b32_dpp v74, v62 quad_perm:[2,3,0,1] row_mask:0xf bank_mask:0xf
	v_mov_b32_dpp v75, v63 quad_perm:[2,3,0,1] row_mask:0xf bank_mask:0xf
	v_mov_b32_dpp v72, v64 quad_perm:[2,3,0,1] row_mask:0xf bank_mask:0xf
	v_mov_b32_dpp v73, v65 quad_perm:[2,3,0,1] row_mask:0xf bank_mask:0xf
	v_cndmask_b32_e64 v62, v62, v72, s[50:51]
	v_cndmask_b32_e64 v63, v63, v73, s[50:51]
	v_cndmask_b32_e64 v64, v74, v64, s[50:51]
	v_cndmask_b32_e64 v65, v75, v65, s[50:51]
	s_nop 1
	v_mov_b32_dpp v72, v59 quad_perm:[1,0,3,2] row_mask:0xf bank_mask:0xf
	v_mov_b32_dpp v73, v58 quad_perm:[1,0,3,2] row_mask:0xf bank_mask:0xf
	v_mov_b32_dpp v74, v61 quad_perm:[1,0,3,2] row_mask:0xf bank_mask:0xf
	v_mov_b32_dpp v75, v60 quad_perm:[1,0,3,2] row_mask:0xf bank_mask:0xf
	v_cndmask_b32_e64 v58, v58, v72, s[36:37]
	v_cndmask_b32_e64 v59, v73, v59, s[36:37]
	v_cndmask_b32_e64 v60, v60, v74, s[36:37]
	v_cndmask_b32_e64 v61, v75, v61, s[36:37]
	s_nop 1
	v_mov_b32_dpp v74, v58 quad_perm:[2,3,0,1] row_mask:0xf bank_mask:0xf
	v_mov_b32_dpp v75, v59 quad_perm:[2,3,0,1] row_mask:0xf bank_mask:0xf
	v_mov_b32_dpp v72, v60 quad_perm:[2,3,0,1] row_mask:0xf bank_mask:0xf
	v_mov_b32_dpp v73, v61 quad_perm:[2,3,0,1] row_mask:0xf bank_mask:0xf
	v_cndmask_b32_e64 v58, v58, v72, s[50:51]
	v_cndmask_b32_e64 v59, v59, v73, s[50:51]
	v_cndmask_b32_e64 v60, v74, v60, s[50:51]
	v_cndmask_b32_e64 v61, v75, v61, s[50:51]
	s_nop 1
	v_mov_b32_dpp v72, v55 quad_perm:[1,0,3,2] row_mask:0xf bank_mask:0xf
	v_mov_b32_dpp v73, v54 quad_perm:[1,0,3,2] row_mask:0xf bank_mask:0xf
	v_mov_b32_dpp v74, v57 quad_perm:[1,0,3,2] row_mask:0xf bank_mask:0xf
	v_mov_b32_dpp v75, v56 quad_perm:[1,0,3,2] row_mask:0xf bank_mask:0xf
	v_cndmask_b32_e64 v54, v54, v72, s[36:37]
	v_cndmask_b32_e64 v55, v73, v55, s[36:37]
	v_cndmask_b32_e64 v56, v56, v74, s[36:37]
	v_cndmask_b32_e64 v57, v75, v57, s[36:37]
	s_nop 1
	v_mov_b32_dpp v74, v54 quad_perm:[2,3,0,1] row_mask:0xf bank_mask:0xf
	v_mov_b32_dpp v75, v55 quad_perm:[2,3,0,1] row_mask:0xf bank_mask:0xf
	v_mov_b32_dpp v72, v56 quad_perm:[2,3,0,1] row_mask:0xf bank_mask:0xf
	v_mov_b32_dpp v73, v57 quad_perm:[2,3,0,1] row_mask:0xf bank_mask:0xf
	v_cndmask_b32_e64 v54, v54, v72, s[50:51]
	v_cndmask_b32_e64 v55, v55, v73, s[50:51]
	v_cndmask_b32_e64 v56, v74, v56, s[50:51]
	v_cndmask_b32_e64 v57, v75, v57, s[50:51]
	s_nop 1
	v_mov_b32_dpp v72, v51 quad_perm:[1,0,3,2] row_mask:0xf bank_mask:0xf
	v_mov_b32_dpp v73, v50 quad_perm:[1,0,3,2] row_mask:0xf bank_mask:0xf
	v_mov_b32_dpp v74, v53 quad_perm:[1,0,3,2] row_mask:0xf bank_mask:0xf
	v_mov_b32_dpp v75, v52 quad_perm:[1,0,3,2] row_mask:0xf bank_mask:0xf
	v_cndmask_b32_e64 v50, v50, v72, s[36:37]
	v_cndmask_b32_e64 v51, v73, v51, s[36:37]
	v_cndmask_b32_e64 v52, v52, v74, s[36:37]
	v_cndmask_b32_e64 v53, v75, v53, s[36:37]
	s_nop 1
	v_mov_b32_dpp v74, v50 quad_perm:[2,3,0,1] row_mask:0xf bank_mask:0xf
	v_mov_b32_dpp v75, v51 quad_perm:[2,3,0,1] row_mask:0xf bank_mask:0xf
	v_mov_b32_dpp v72, v52 quad_perm:[2,3,0,1] row_mask:0xf bank_mask:0xf
	v_mov_b32_dpp v73, v53 quad_perm:[2,3,0,1] row_mask:0xf bank_mask:0xf
	v_cndmask_b32_e64 v50, v50, v72, s[50:51]
	v_cndmask_b32_e64 v51, v51, v73, s[50:51]
	v_cndmask_b32_e64 v52, v74, v52, s[50:51]
	v_cndmask_b32_e64 v53, v75, v53, s[50:51]
	s_nop 1
	v_mov_b32_dpp v72, v47 quad_perm:[1,0,3,2] row_mask:0xf bank_mask:0xf
	v_mov_b32_dpp v73, v46 quad_perm:[1,0,3,2] row_mask:0xf bank_mask:0xf
	v_mov_b32_dpp v74, v49 quad_perm:[1,0,3,2] row_mask:0xf bank_mask:0xf
	v_mov_b32_dpp v75, v48 quad_perm:[1,0,3,2] row_mask:0xf bank_mask:0xf
	v_cndmask_b32_e64 v46, v46, v72, s[36:37]
	v_cndmask_b32_e64 v47, v73, v47, s[36:37]
	v_cndmask_b32_e64 v48, v48, v74, s[36:37]
	v_cndmask_b32_e64 v49, v75, v49, s[36:37]
	s_nop 1
	v_mov_b32_dpp v74, v46 quad_perm:[2,3,0,1] row_mask:0xf bank_mask:0xf
	v_mov_b32_dpp v75, v47 quad_perm:[2,3,0,1] row_mask:0xf bank_mask:0xf
	v_mov_b32_dpp v72, v48 quad_perm:[2,3,0,1] row_mask:0xf bank_mask:0xf
	v_mov_b32_dpp v73, v49 quad_perm:[2,3,0,1] row_mask:0xf bank_mask:0xf
	v_cndmask_b32_e64 v46, v46, v72, s[50:51]
	v_cndmask_b32_e64 v47, v47, v73, s[50:51]
	v_cndmask_b32_e64 v48, v74, v48, s[50:51]
	v_cndmask_b32_e64 v49, v75, v49, s[50:51]
	s_nop 1
	v_mov_b32_dpp v72, v43 quad_perm:[1,0,3,2] row_mask:0xf bank_mask:0xf
	v_mov_b32_dpp v73, v42 quad_perm:[1,0,3,2] row_mask:0xf bank_mask:0xf
	v_mov_b32_dpp v74, v45 quad_perm:[1,0,3,2] row_mask:0xf bank_mask:0xf
	v_mov_b32_dpp v75, v44 quad_perm:[1,0,3,2] row_mask:0xf bank_mask:0xf
	v_cndmask_b32_e64 v42, v42, v72, s[36:37]
	v_cndmask_b32_e64 v43, v73, v43, s[36:37]
	v_cndmask_b32_e64 v44, v44, v74, s[36:37]
	v_cndmask_b32_e64 v45, v75, v45, s[36:37]
	s_nop 1
	v_mov_b32_dpp v74, v42 quad_perm:[2,3,0,1] row_mask:0xf bank_mask:0xf
	v_mov_b32_dpp v75, v43 quad_perm:[2,3,0,1] row_mask:0xf bank_mask:0xf
	v_mov_b32_dpp v72, v44 quad_perm:[2,3,0,1] row_mask:0xf bank_mask:0xf
	v_mov_b32_dpp v73, v45 quad_perm:[2,3,0,1] row_mask:0xf bank_mask:0xf
	v_cndmask_b32_e64 v42, v42, v72, s[50:51]
	v_cndmask_b32_e64 v43, v43, v73, s[50:51]
	v_cndmask_b32_e64 v44, v74, v44, s[50:51]
	v_cndmask_b32_e64 v45, v75, v45, s[50:51]
	s_nop 1
	v_mov_b32_dpp v72, v39 quad_perm:[1,0,3,2] row_mask:0xf bank_mask:0xf
	v_mov_b32_dpp v73, v38 quad_perm:[1,0,3,2] row_mask:0xf bank_mask:0xf
	v_mov_b32_dpp v74, v41 quad_perm:[1,0,3,2] row_mask:0xf bank_mask:0xf
	v_mov_b32_dpp v75, v40 quad_perm:[1,0,3,2] row_mask:0xf bank_mask:0xf
	v_cndmask_b32_e64 v38, v38, v72, s[36:37]
	v_cndmask_b32_e64 v39, v73, v39, s[36:37]
	v_cndmask_b32_e64 v40, v40, v74, s[36:37]
	v_cndmask_b32_e64 v41, v75, v41, s[36:37]
	s_nop 1
	v_mov_b32_dpp v74, v38 quad_perm:[2,3,0,1] row_mask:0xf bank_mask:0xf
	v_mov_b32_dpp v75, v39 quad_perm:[2,3,0,1] row_mask:0xf bank_mask:0xf
	v_mov_b32_dpp v72, v40 quad_perm:[2,3,0,1] row_mask:0xf bank_mask:0xf
	v_mov_b32_dpp v73, v41 quad_perm:[2,3,0,1] row_mask:0xf bank_mask:0xf
	v_cndmask_b32_e64 v38, v38, v72, s[50:51]
	v_cndmask_b32_e64 v39, v39, v73, s[50:51]
	v_cndmask_b32_e64 v40, v74, v40, s[50:51]
	v_cndmask_b32_e64 v41, v75, v41, s[50:51]
	s_nop 1
	v_mov_b32_dpp v72, v35 quad_perm:[1,0,3,2] row_mask:0xf bank_mask:0xf
	v_mov_b32_dpp v73, v34 quad_perm:[1,0,3,2] row_mask:0xf bank_mask:0xf
	v_mov_b32_dpp v74, v37 quad_perm:[1,0,3,2] row_mask:0xf bank_mask:0xf
	v_mov_b32_dpp v75, v36 quad_perm:[1,0,3,2] row_mask:0xf bank_mask:0xf
	v_cndmask_b32_e64 v34, v34, v72, s[36:37]
	v_cndmask_b32_e64 v35, v73, v35, s[36:37]
	v_cndmask_b32_e64 v36, v36, v74, s[36:37]
	v_cndmask_b32_e64 v37, v75, v37, s[36:37]
	s_nop 1
	v_mov_b32_dpp v74, v34 quad_perm:[2,3,0,1] row_mask:0xf bank_mask:0xf
	v_mov_b32_dpp v75, v35 quad_perm:[2,3,0,1] row_mask:0xf bank_mask:0xf
	v_mov_b32_dpp v72, v36 quad_perm:[2,3,0,1] row_mask:0xf bank_mask:0xf
	v_mov_b32_dpp v73, v37 quad_perm:[2,3,0,1] row_mask:0xf bank_mask:0xf
	v_cndmask_b32_e64 v34, v34, v72, s[50:51]
	v_cndmask_b32_e64 v35, v35, v73, s[50:51]
	v_cndmask_b32_e64 v36, v74, v36, s[50:51]
	v_cndmask_b32_e64 v37, v75, v37, s[50:51]
	v_cvt_pk_bf16_f32 v62, v62, v63
	v_cvt_pk_bf16_f32 v63, v64, v65
	ds_write_b64 v209, v[62:63] offset:0
	v_cvt_pk_bf16_f32 v58, v58, v59
	v_cvt_pk_bf16_f32 v59, v60, v61
	ds_write_b64 v210, v[58:59] offset:0
	v_cvt_pk_bf16_f32 v54, v54, v55
	v_cvt_pk_bf16_f32 v55, v56, v57
	ds_write_b64 v211, v[54:55] offset:0
	v_cvt_pk_bf16_f32 v50, v50, v51
	v_cvt_pk_bf16_f32 v51, v52, v53
	ds_write_b64 v212, v[50:51] offset:0
	v_cvt_pk_bf16_f32 v46, v46, v47
	v_cvt_pk_bf16_f32 v47, v48, v49
	ds_write_b64 v209, v[46:47] offset:2048
	v_cvt_pk_bf16_f32 v42, v42, v43
	v_cvt_pk_bf16_f32 v43, v44, v45
	ds_write_b64 v210, v[42:43] offset:2048
	v_cvt_pk_bf16_f32 v38, v38, v39
	v_cvt_pk_bf16_f32 v39, v40, v41
	ds_write_b64 v211, v[38:39] offset:2048
	v_cvt_pk_bf16_f32 v34, v34, v35
	v_cvt_pk_bf16_f32 v35, v36, v37
	ds_write_b64 v212, v[34:35] offset:2048
	s_waitcnt lgkmcnt(0)
	ds_read_b128 v[76:79], v213 offset:0
	ds_read_b128 v[80:83], v213 offset:1024
	ds_read_b128 v[84:87], v213 offset:2048
	ds_read_b128 v[88:91], v213 offset:3072
	s_waitcnt lgkmcnt(3)
	global_store_dwordx4 v214, v[76:79], s[16:17] sc1
	s_waitcnt lgkmcnt(2)
	v_add_u32_e32 v216, 0x10000, v214
	global_store_dwordx4 v216, v[80:83], s[16:17] sc1
	s_waitcnt lgkmcnt(1)
	v_add_u32_e32 v216, 0x20000, v214
	global_store_dwordx4 v216, v[84:87], s[16:17] sc1
	s_waitcnt lgkmcnt(0)
	v_add_u32_e32 v216, 0x30000, v214
	global_store_dwordx4 v216, v[88:91], s[16:17] sc1
	s_nop 1
	v_max_f32_e32 v30, 0, v30
	v_max_f32_e32 v31, 0, v31
	v_max_f32_e32 v32, 0, v32
	v_max_f32_e32 v33, 0, v33
	v_mul_f32_e32 v30, v30, v30
	v_mul_f32_e32 v31, v31, v31
	v_mul_f32_e32 v32, v32, v32
	v_mul_f32_e32 v33, v33, v33
	v_max_f32_e32 v26, 0, v26
	v_max_f32_e32 v27, 0, v27
	v_max_f32_e32 v28, 0, v28
	v_max_f32_e32 v29, 0, v29
	v_mul_f32_e32 v26, v26, v26
	v_mul_f32_e32 v27, v27, v27
	v_mul_f32_e32 v28, v28, v28
	v_mul_f32_e32 v29, v29, v29
	v_max_f32_e32 v22, 0, v22
	v_max_f32_e32 v23, 0, v23
	v_max_f32_e32 v24, 0, v24
	v_max_f32_e32 v25, 0, v25
	v_mul_f32_e32 v22, v22, v22
	v_mul_f32_e32 v23, v23, v23
	v_mul_f32_e32 v24, v24, v24
	v_mul_f32_e32 v25, v25, v25
	v_max_f32_e32 v18, 0, v18
	v_max_f32_e32 v19, 0, v19
	v_max_f32_e32 v20, 0, v20
	v_max_f32_e32 v21, 0, v21
	v_mul_f32_e32 v18, v18, v18
	v_mul_f32_e32 v19, v19, v19
	v_mul_f32_e32 v20, v20, v20
	v_mul_f32_e32 v21, v21, v21
	v_max_f32_e32 v14, 0, v14
	v_max_f32_e32 v15, 0, v15
	v_max_f32_e32 v16, 0, v16
	v_max_f32_e32 v17, 0, v17
	v_mul_f32_e32 v14, v14, v14
	v_mul_f32_e32 v15, v15, v15
	v_mul_f32_e32 v16, v16, v16
	v_mul_f32_e32 v17, v17, v17
	v_max_f32_e32 v10, 0, v10
	v_max_f32_e32 v11, 0, v11
	v_max_f32_e32 v12, 0, v12
	v_max_f32_e32 v13, 0, v13
	v_mul_f32_e32 v10, v10, v10
	v_mul_f32_e32 v11, v11, v11
	v_mul_f32_e32 v12, v12, v12
	v_mul_f32_e32 v13, v13, v13
	v_max_f32_e32 v6, 0, v6
	v_max_f32_e32 v7, 0, v7
	v_max_f32_e32 v8, 0, v8
	v_max_f32_e32 v9, 0, v9
	v_mul_f32_e32 v6, v6, v6
	v_mul_f32_e32 v7, v7, v7
	v_mul_f32_e32 v8, v8, v8
	v_mul_f32_e32 v9, v9, v9
	v_max_f32_e32 v2, 0, v2
	v_max_f32_e32 v3, 0, v3
	v_max_f32_e32 v4, 0, v4
	v_max_f32_e32 v5, 0, v5
	v_mul_f32_e32 v2, v2, v2
	v_mul_f32_e32 v3, v3, v3
	v_mul_f32_e32 v4, v4, v4
	v_mul_f32_e32 v5, v5, v5
	s_nop 1
	v_mov_b32_dpp v72, v31 quad_perm:[1,0,3,2] row_mask:0xf bank_mask:0xf
	v_mov_b32_dpp v73, v30 quad_perm:[1,0,3,2] row_mask:0xf bank_mask:0xf
	v_mov_b32_dpp v74, v33 quad_perm:[1,0,3,2] row_mask:0xf bank_mask:0xf
	v_mov_b32_dpp v75, v32 quad_perm:[1,0,3,2] row_mask:0xf bank_mask:0xf
	v_cndmask_b32_e64 v30, v30, v72, s[36:37]
	v_cndmask_b32_e64 v31, v73, v31, s[36:37]
	v_cndmask_b32_e64 v32, v32, v74, s[36:37]
	v_cndmask_b32_e64 v33, v75, v33, s[36:37]
	s_nop 1
	v_mov_b32_dpp v74, v30 quad_perm:[2,3,0,1] row_mask:0xf bank_mask:0xf
	v_mov_b32_dpp v75, v31 quad_perm:[2,3,0,1] row_mask:0xf bank_mask:0xf
	v_mov_b32_dpp v72, v32 quad_perm:[2,3,0,1] row_mask:0xf bank_mask:0xf
	v_mov_b32_dpp v73, v33 quad_perm:[2,3,0,1] row_mask:0xf bank_mask:0xf
	v_cndmask_b32_e64 v30, v30, v72, s[50:51]
	v_cndmask_b32_e64 v31, v31, v73, s[50:51]
	v_cndmask_b32_e64 v32, v74, v32, s[50:51]
	v_cndmask_b32_e64 v33, v75, v33, s[50:51]
	s_nop 1
	v_mov_b32_dpp v72, v27 quad_perm:[1,0,3,2] row_mask:0xf bank_mask:0xf
	v_mov_b32_dpp v73, v26 quad_perm:[1,0,3,2] row_mask:0xf bank_mask:0xf
	v_mov_b32_dpp v74, v29 quad_perm:[1,0,3,2] row_mask:0xf bank_mask:0xf
	v_mov_b32_dpp v75, v28 quad_perm:[1,0,3,2] row_mask:0xf bank_mask:0xf
	v_cndmask_b32_e64 v26, v26, v72, s[36:37]
	v_cndmask_b32_e64 v27, v73, v27, s[36:37]
	v_cndmask_b32_e64 v28, v28, v74, s[36:37]
	v_cndmask_b32_e64 v29, v75, v29, s[36:37]
	s_nop 1
	v_mov_b32_dpp v74, v26 quad_perm:[2,3,0,1] row_mask:0xf bank_mask:0xf
	v_mov_b32_dpp v75, v27 quad_perm:[2,3,0,1] row_mask:0xf bank_mask:0xf
	v_mov_b32_dpp v72, v28 quad_perm:[2,3,0,1] row_mask:0xf bank_mask:0xf
	v_mov_b32_dpp v73, v29 quad_perm:[2,3,0,1] row_mask:0xf bank_mask:0xf
	v_cndmask_b32_e64 v26, v26, v72, s[50:51]
	v_cndmask_b32_e64 v27, v27, v73, s[50:51]
	v_cndmask_b32_e64 v28, v74, v28, s[50:51]
	v_cndmask_b32_e64 v29, v75, v29, s[50:51]
	s_nop 1
	v_mov_b32_dpp v72, v23 quad_perm:[1,0,3,2] row_mask:0xf bank_mask:0xf
	v_mov_b32_dpp v73, v22 quad_perm:[1,0,3,2] row_mask:0xf bank_mask:0xf
	v_mov_b32_dpp v74, v25 quad_perm:[1,0,3,2] row_mask:0xf bank_mask:0xf
	v_mov_b32_dpp v75, v24 quad_perm:[1,0,3,2] row_mask:0xf bank_mask:0xf
	v_cndmask_b32_e64 v22, v22, v72, s[36:37]
	v_cndmask_b32_e64 v23, v73, v23, s[36:37]
	v_cndmask_b32_e64 v24, v24, v74, s[36:37]
	v_cndmask_b32_e64 v25, v75, v25, s[36:37]
	s_nop 1
	v_mov_b32_dpp v74, v22 quad_perm:[2,3,0,1] row_mask:0xf bank_mask:0xf
	v_mov_b32_dpp v75, v23 quad_perm:[2,3,0,1] row_mask:0xf bank_mask:0xf
	v_mov_b32_dpp v72, v24 quad_perm:[2,3,0,1] row_mask:0xf bank_mask:0xf
	v_mov_b32_dpp v73, v25 quad_perm:[2,3,0,1] row_mask:0xf bank_mask:0xf
	v_cndmask_b32_e64 v22, v22, v72, s[50:51]
	v_cndmask_b32_e64 v23, v23, v73, s[50:51]
	v_cndmask_b32_e64 v24, v74, v24, s[50:51]
	v_cndmask_b32_e64 v25, v75, v25, s[50:51]
	s_nop 1
	v_mov_b32_dpp v72, v19 quad_perm:[1,0,3,2] row_mask:0xf bank_mask:0xf
	v_mov_b32_dpp v73, v18 quad_perm:[1,0,3,2] row_mask:0xf bank_mask:0xf
	v_mov_b32_dpp v74, v21 quad_perm:[1,0,3,2] row_mask:0xf bank_mask:0xf
	v_mov_b32_dpp v75, v20 quad_perm:[1,0,3,2] row_mask:0xf bank_mask:0xf
	v_cndmask_b32_e64 v18, v18, v72, s[36:37]
	v_cndmask_b32_e64 v19, v73, v19, s[36:37]
	v_cndmask_b32_e64 v20, v20, v74, s[36:37]
	v_cndmask_b32_e64 v21, v75, v21, s[36:37]
	s_nop 1
	v_mov_b32_dpp v74, v18 quad_perm:[2,3,0,1] row_mask:0xf bank_mask:0xf
	v_mov_b32_dpp v75, v19 quad_perm:[2,3,0,1] row_mask:0xf bank_mask:0xf
	v_mov_b32_dpp v72, v20 quad_perm:[2,3,0,1] row_mask:0xf bank_mask:0xf
	v_mov_b32_dpp v73, v21 quad_perm:[2,3,0,1] row_mask:0xf bank_mask:0xf
	v_cndmask_b32_e64 v18, v18, v72, s[50:51]
	v_cndmask_b32_e64 v19, v19, v73, s[50:51]
	v_cndmask_b32_e64 v20, v74, v20, s[50:51]
	v_cndmask_b32_e64 v21, v75, v21, s[50:51]
	s_nop 1
	v_mov_b32_dpp v72, v15 quad_perm:[1,0,3,2] row_mask:0xf bank_mask:0xf
	v_mov_b32_dpp v73, v14 quad_perm:[1,0,3,2] row_mask:0xf bank_mask:0xf
	v_mov_b32_dpp v74, v17 quad_perm:[1,0,3,2] row_mask:0xf bank_mask:0xf
	v_mov_b32_dpp v75, v16 quad_perm:[1,0,3,2] row_mask:0xf bank_mask:0xf
	v_cndmask_b32_e64 v14, v14, v72, s[36:37]
	v_cndmask_b32_e64 v15, v73, v15, s[36:37]
	v_cndmask_b32_e64 v16, v16, v74, s[36:37]
	v_cndmask_b32_e64 v17, v75, v17, s[36:37]
	s_nop 1
	v_mov_b32_dpp v74, v14 quad_perm:[2,3,0,1] row_mask:0xf bank_mask:0xf
	v_mov_b32_dpp v75, v15 quad_perm:[2,3,0,1] row_mask:0xf bank_mask:0xf
	v_mov_b32_dpp v72, v16 quad_perm:[2,3,0,1] row_mask:0xf bank_mask:0xf
	v_mov_b32_dpp v73, v17 quad_perm:[2,3,0,1] row_mask:0xf bank_mask:0xf
	v_cndmask_b32_e64 v14, v14, v72, s[50:51]
	v_cndmask_b32_e64 v15, v15, v73, s[50:51]
	v_cndmask_b32_e64 v16, v74, v16, s[50:51]
	v_cndmask_b32_e64 v17, v75, v17, s[50:51]
	s_nop 1
	v_mov_b32_dpp v72, v11 quad_perm:[1,0,3,2] row_mask:0xf bank_mask:0xf
	v_mov_b32_dpp v73, v10 quad_perm:[1,0,3,2] row_mask:0xf bank_mask:0xf
	v_mov_b32_dpp v74, v13 quad_perm:[1,0,3,2] row_mask:0xf bank_mask:0xf
	v_mov_b32_dpp v75, v12 quad_perm:[1,0,3,2] row_mask:0xf bank_mask:0xf
	v_cndmask_b32_e64 v10, v10, v72, s[36:37]
	v_cndmask_b32_e64 v11, v73, v11, s[36:37]
	v_cndmask_b32_e64 v12, v12, v74, s[36:37]
	v_cndmask_b32_e64 v13, v75, v13, s[36:37]
	s_nop 1
	v_mov_b32_dpp v74, v10 quad_perm:[2,3,0,1] row_mask:0xf bank_mask:0xf
	v_mov_b32_dpp v75, v11 quad_perm:[2,3,0,1] row_mask:0xf bank_mask:0xf
	v_mov_b32_dpp v72, v12 quad_perm:[2,3,0,1] row_mask:0xf bank_mask:0xf
	v_mov_b32_dpp v73, v13 quad_perm:[2,3,0,1] row_mask:0xf bank_mask:0xf
	v_cndmask_b32_e64 v10, v10, v72, s[50:51]
	v_cndmask_b32_e64 v11, v11, v73, s[50:51]
	v_cndmask_b32_e64 v12, v74, v12, s[50:51]
	v_cndmask_b32_e64 v13, v75, v13, s[50:51]
	s_nop 1
	v_mov_b32_dpp v72, v7 quad_perm:[1,0,3,2] row_mask:0xf bank_mask:0xf
	v_mov_b32_dpp v73, v6 quad_perm:[1,0,3,2] row_mask:0xf bank_mask:0xf
	v_mov_b32_dpp v74, v9 quad_perm:[1,0,3,2] row_mask:0xf bank_mask:0xf
	v_mov_b32_dpp v75, v8 quad_perm:[1,0,3,2] row_mask:0xf bank_mask:0xf
	v_cndmask_b32_e64 v6, v6, v72, s[36:37]
	v_cndmask_b32_e64 v7, v73, v7, s[36:37]
	v_cndmask_b32_e64 v8, v8, v74, s[36:37]
	v_cndmask_b32_e64 v9, v75, v9, s[36:37]
	s_nop 1
	v_mov_b32_dpp v74, v6 quad_perm:[2,3,0,1] row_mask:0xf bank_mask:0xf
	v_mov_b32_dpp v75, v7 quad_perm:[2,3,0,1] row_mask:0xf bank_mask:0xf
	v_mov_b32_dpp v72, v8 quad_perm:[2,3,0,1] row_mask:0xf bank_mask:0xf
	v_mov_b32_dpp v73, v9 quad_perm:[2,3,0,1] row_mask:0xf bank_mask:0xf
	v_cndmask_b32_e64 v6, v6, v72, s[50:51]
	v_cndmask_b32_e64 v7, v7, v73, s[50:51]
	v_cndmask_b32_e64 v8, v74, v8, s[50:51]
	v_cndmask_b32_e64 v9, v75, v9, s[50:51]
	s_nop 1
	v_mov_b32_dpp v72, v3 quad_perm:[1,0,3,2] row_mask:0xf bank_mask:0xf
	v_mov_b32_dpp v73, v2 quad_perm:[1,0,3,2] row_mask:0xf bank_mask:0xf
	v_mov_b32_dpp v74, v5 quad_perm:[1,0,3,2] row_mask:0xf bank_mask:0xf
	v_mov_b32_dpp v75, v4 quad_perm:[1,0,3,2] row_mask:0xf bank_mask:0xf
	v_cndmask_b32_e64 v2, v2, v72, s[36:37]
	v_cndmask_b32_e64 v3, v73, v3, s[36:37]
	v_cndmask_b32_e64 v4, v4, v74, s[36:37]
	v_cndmask_b32_e64 v5, v75, v5, s[36:37]
	s_nop 1
	v_mov_b32_dpp v74, v2 quad_perm:[2,3,0,1] row_mask:0xf bank_mask:0xf
	v_mov_b32_dpp v75, v3 quad_perm:[2,3,0,1] row_mask:0xf bank_mask:0xf
	v_mov_b32_dpp v72, v4 quad_perm:[2,3,0,1] row_mask:0xf bank_mask:0xf
	v_mov_b32_dpp v73, v5 quad_perm:[2,3,0,1] row_mask:0xf bank_mask:0xf
	v_cndmask_b32_e64 v2, v2, v72, s[50:51]
	v_cndmask_b32_e64 v3, v3, v73, s[50:51]
	v_cndmask_b32_e64 v4, v74, v4, s[50:51]
	v_cndmask_b32_e64 v5, v75, v5, s[50:51]
	s_waitcnt lgkmcnt(0)
	v_cvt_pk_bf16_f32 v30, v30, v31
	v_cvt_pk_bf16_f32 v31, v32, v33
	ds_write_b64 v209, v[30:31] offset:0
	v_cvt_pk_bf16_f32 v26, v26, v27
	v_cvt_pk_bf16_f32 v27, v28, v29
	ds_write_b64 v210, v[26:27] offset:0
	v_cvt_pk_bf16_f32 v22, v22, v23
	v_cvt_pk_bf16_f32 v23, v24, v25
	ds_write_b64 v211, v[22:23] offset:0
	v_cvt_pk_bf16_f32 v18, v18, v19
	v_cvt_pk_bf16_f32 v19, v20, v21
	ds_write_b64 v212, v[18:19] offset:0
	v_cvt_pk_bf16_f32 v14, v14, v15
	v_cvt_pk_bf16_f32 v15, v16, v17
	ds_write_b64 v209, v[14:15] offset:2048
	v_cvt_pk_bf16_f32 v10, v10, v11
	v_cvt_pk_bf16_f32 v11, v12, v13
	ds_write_b64 v210, v[10:11] offset:2048
	v_cvt_pk_bf16_f32 v6, v6, v7
	v_cvt_pk_bf16_f32 v7, v8, v9
	ds_write_b64 v211, v[6:7] offset:2048
	v_cvt_pk_bf16_f32 v2, v2, v3
	v_cvt_pk_bf16_f32 v3, v4, v5
	ds_write_b64 v212, v[2:3] offset:2048
	s_waitcnt lgkmcnt(0)
	ds_read_b128 v[76:79], v213 offset:0
	ds_read_b128 v[80:83], v213 offset:1024
	ds_read_b128 v[84:87], v213 offset:2048
	ds_read_b128 v[88:91], v213 offset:3072
	s_waitcnt lgkmcnt(3)
	v_add_u32_e32 v216, 0x40000, v214
	global_store_dwordx4 v216, v[76:79], s[16:17] sc1
	s_waitcnt lgkmcnt(2)
	v_add_u32_e32 v216, 0x50000, v214
	global_store_dwordx4 v216, v[80:83], s[16:17] sc1
	s_waitcnt lgkmcnt(1)
	v_add_u32_e32 v216, 0x60000, v214
	global_store_dwordx4 v216, v[84:87], s[16:17] sc1
	s_waitcnt lgkmcnt(0)
	v_add_u32_e32 v216, 0x70000, v214
	global_store_dwordx4 v216, v[88:91], s[16:17] sc1
	s_nop 1
	s_and_b64 vcc, exec, s[34:35]
	s_cbranch_vccnz .Lrelu2_nost2
	s_mov_b64 s[16:17], 0x100
	s_mov_b64 s[36:37], 0x4100
	s_mov_b64 s[38:39], 0x8100
	v_lshl_add_u64 v[70:71], v[66:67], 0, s[16:17]
	s_add_i32 m0, s8, 0x18000
	s_nop 0
	global_load_lds_dwordx4 v[70:71], off sc1
	v_lshl_add_u64 v[70:71], v[66:67], 0, s[36:37]
	s_mov_b32 m0, s45
	s_nop 0
	global_load_lds_dwordx4 v[70:71], off sc1
	v_lshl_add_u64 v[70:71], v[66:67], 0, s[38:39]
	s_mov_b32 m0, s46
	s_mov_b64 s[38:39], 0xc100
	global_load_lds_dwordx4 v[70:71], off sc1
	v_lshl_add_u64 v[66:67], v[66:67], 0, s[38:39]
	s_mov_b32 m0, s47
	s_nop 0
	global_load_lds_dwordx4 v[66:67], off sc1
	v_lshl_add_u64 v[66:67], v[68:69], 0, s[16:17]
	s_add_i32 m0, s9, 0x20000
	s_nop 0
	global_load_lds_dwordx4 v[66:67], off sc1
	v_lshl_add_u64 v[66:67], v[68:69], 0, s[36:37]
	s_mov_b32 m0, s48
	s_nop 0
	global_load_lds_dwordx4 v[66:67], off sc1

.LBB0_81:
	s_mul_hi_i32 s6, s49, 0x2aaaaaab
	s_lshr_b32 s14, s6, 31
	s_ashr_i32 s6, s6, 2
	s_add_i32 s6, s6, s14
	s_mul_i32 s14, s6, 24
	s_sub_i32 s14, s49, s14
	s_lshl_b32 s26, s14, 8
	s_lshl_b32 s22, s6, 7
	s_ashr_i32 s27, s26, 31
	s_ashr_i32 s23, s22, 31
	s_lshl_b64 s[34:35], s[26:27], 11
	s_lshl_b64 s[36:37], s[22:23], 11
	s_and_b64 vcc, exec, s[38:39]
	s_cbranch_vccnz .Lrelu2_pf
	v_readlane_b32 s52, v255, 40
	s_add_i32 s52, s52, 0x5d0e1000
	s_lshl_b32 s53, s14, 7
	s_add_u32 s64, s94, 0xcbc8000
	s_addc_u32 s65, s95, 0
	v_and_b32_e32 v226, 7, v137
	v_lshlrev_b32_e32 v226, 4, v226
	v_add_u32_e32 v226, s53, v226
	s_mov_b32 s53, 0x100000
.Lm1poll_a:
	global_load_dwordx4 v[228:231], v226, s[64:65] sc1
	s_waitcnt vmcnt(0)
	v_cmp_ne_u32_e32 vcc, s52, v228
	s_cbranch_vccz .Lm1ok_a
	s_sleep 1
	s_add_i32 s53, s53, -1
	s_cmp_lg_u32 s53, 0
	s_cbranch_scc1 .Lm1poll_a
.Lm1ok_a:
	s_mov_b32 m0, s8
	v_lshl_add_u64 v[2:3], v[102:103], 0, s[34:35]
	global_load_lds_dwordx4 v[2:3], off sc1
	v_lshl_add_u64 v[6:7], v[2:3], 0, s[30:31]
	s_mov_b32 m0, s11
	s_mov_b64 s[16:17], 0xc000
	global_load_lds_dwordx4 v[6:7], off sc1
	v_lshl_add_u64 v[6:7], v[2:3], 0, s[24:25]
	s_add_i32 m0, s8, 0x800
	v_lshl_add_u64 v[4:5], v[106:107], 0, s[36:37]
	global_load_lds_dwordx4 v[6:7], off sc1
	v_lshl_add_u64 v[6:7], v[2:3], 0, s[16:17]
	s_mov_b32 m0, s12
	s_mov_b64 s[16:17], 0x4080
	global_load_lds_dwordx4 v[6:7], off sc1
	s_mov_b32 m0, s13
	v_lshl_add_u64 v[6:7], v[4:5], 0, s[30:31]
	global_load_lds_dwordx4 v[4:5], off sc1
	s_mov_b32 m0, s40
	s_mov_b64 s[38:39], 0x8080
	global_load_lds_dwordx4 v[6:7], off sc1
	v_lshl_add_u64 v[6:7], v[2:3], 0, s[2:3]
	s_add_i32 m0, s8, 0xc000
	s_mov_b64 s[50:51], 0x8100
	global_load_lds_dwordx4 v[6:7], off sc1
	v_lshl_add_u64 v[6:7], v[2:3], 0, s[16:17]
	s_mov_b32 m0, s41
	s_nop 0
	global_load_lds_dwordx4 v[6:7], off sc1
	v_lshl_add_u64 v[6:7], v[2:3], 0, s[38:39]
	s_mov_b32 m0, s42
	s_mov_b64 s[38:39], 0xc080
	global_load_lds_dwordx4 v[6:7], off sc1
	v_lshl_add_u64 v[6:7], v[2:3], 0, s[38:39]
	s_mov_b32 m0, s43
	s_mov_b64 s[38:39], 0x4100
	global_load_lds_dwordx4 v[6:7], off sc1
	v_lshl_add_u64 v[6:7], v[4:5], 0, s[2:3]
	s_add_i32 m0, s9, 0x14000
	s_nop 0
	global_load_lds_dwordx4 v[6:7], off sc1
	v_lshl_add_u64 v[6:7], v[4:5], 0, s[16:17]
	s_mov_b32 m0, s44
	s_mov_b64 s[16:17], 0x100
	global_load_lds_dwordx4 v[6:7], off sc1
	v_lshl_add_u64 v[6:7], v[2:3], 0, s[16:17]
	s_add_i32 m0, s8, 0x18000
	s_nop 0
	global_load_lds_dwordx4 v[6:7], off sc1
	v_lshl_add_u64 v[6:7], v[2:3], 0, s[38:39]
	s_mov_b32 m0, s45
	s_nop 0
	global_load_lds_dwordx4 v[6:7], off sc1
	v_lshl_add_u64 v[6:7], v[2:3], 0, s[50:51]
	s_mov_b32 m0, s46
	s_mov_b64 s[50:51], 0xc100
	global_load_lds_dwordx4 v[6:7], off sc1
	v_lshl_add_u64 v[2:3], v[2:3], 0, s[50:51]
	s_mov_b32 m0, s47
	s_nop 0
	global_load_lds_dwordx4 v[2:3], off sc1
	v_lshl_add_u64 v[2:3], v[4:5], 0, s[16:17]
	s_add_i32 m0, s9, 0x20000
	s_nop 0
	global_load_lds_dwordx4 v[2:3], off sc1
	v_lshl_add_u64 v[2:3], v[4:5], 0, s[38:39]
	s_mov_b32 m0, s48
	s_nop 0
	global_load_lds_dwordx4 v[2:3], off sc1
	s_branch .LBB0_83

.LBB0_84:
	s_mul_hi_u32 s34, s27, 0xaaaaaaab
	s_lshr_b32 s34, s34, 1
	s_mul_i32 s34, s34, 0x24000
	s_waitcnt lgkmcnt(0)
	v_mfma_f32_16x16x32_bf16 v[82:85], v[26:29], v[22:25], v[82:85]
	v_add_u32_e32 v191, s14, v99
	s_mul_hi_u32 s35, s19, 0xaaaaaaab
	s_lshr_b32 s35, s35, 1
	v_mfma_f32_16x16x32_bf16 v[78:81], v[26:29], v[18:21], v[78:81]
	s_mul_i32 s35, s35, 0x24000
	v_subrev_u32_e32 v180, s35, v128
	v_subrev_u32_e32 v181, s35, v129
	v_mfma_f32_16x16x32_bf16 v[74:77], v[26:29], v[10:13], v[74:77]
	v_subrev_u32_e32 v182, s35, v130
	v_mfma_f32_16x16x32_bf16 v[70:73], v[26:29], v[6:9], v[70:73]
	v_subrev_u32_e32 v26, s34, v127
	v_mfma_f32_16x16x32_bf16 v[66:69], v[14:17], v[22:25], v[66:69]
	v_mfma_f32_16x16x32_bf16 v[62:65], v[14:17], v[18:21], v[62:65]
	v_mfma_f32_16x16x32_bf16 v[58:61], v[14:17], v[10:13], v[58:61]
	v_mfma_f32_16x16x32_bf16 v[54:57], v[14:17], v[6:9], v[54:57]
	v_subrev_u32_e32 v14, s34, v131
	v_add_u32_e32 v16, v191, v26
	v_add_u32_e32 v14, v191, v14
	v_mfma_f32_16x16x32_bf16 v[38:41], v[30:33], v[22:25], v[38:41]
	v_subrev_u32_e32 v15, s35, v132
	v_mfma_f32_16x16x32_bf16 v[50:53], v[2:5], v[22:25], v[50:53]
	ds_read_b128 v[22:25], v16
	ds_read_b128 v[176:179], v16 offset:2048
	ds_read_b128 v[202:205], v16 offset:4096
	ds_read_b128 v[206:209], v16 offset:6144
	ds_read_b128 v[210:213], v14 offset:32768
	ds_read_b128 v[214:217], v14 offset:34816
	ds_read_b128 v[218:221], v14 offset:36864
	ds_read_b128 v[222:225], v14 offset:38912
	v_mfma_f32_16x16x32_bf16 v[90:93], v[30:33], v[18:21], v[90:93]
	v_mfma_f32_16x16x32_bf16 v[86:89], v[30:33], v[10:13], v[86:89]
	v_mfma_f32_16x16x32_bf16 v[94:97], v[30:33], v[6:9], v[94:97]
	v_mfma_f32_16x16x32_bf16 v[46:49], v[2:5], v[18:21], v[46:49]
	v_mfma_f32_16x16x32_bf16 v[42:45], v[2:5], v[10:13], v[42:45]
	v_mfma_f32_16x16x32_bf16 v[34:37], v[2:5], v[6:9], v[34:37]
	s_add_i32 s34, s6, 4
	s_mul_i32 s35, s34, 0xab
	s_bfe_u32 s35, s35, 0x70009
	s_mul_i32 s35, s35, 3
	s_sub_i32 s34, s34, s35
	s_and_b32 s34, s34, 0xff
	s_mul_i32 s36, s34, 0xc000
	s_waitcnt vmcnt(6)
	v_add_u32_e32 v2, v191, v15
	v_add_u32_e32 v6, v191, v182
	s_waitcnt lgkmcnt(0)
	v_mfma_f32_16x16x32_bf16 v[82:85], v[176:179], v[210:213], v[82:85]
	s_add_i32 s34, s36, s8
	s_waitcnt lgkmcnt(0)
	s_barrier
	v_mfma_f32_16x16x32_bf16 v[78:81], v[176:179], v[214:217], v[78:81]
	ds_read_b128 v[30:33], v2
	ds_read_b128 v[26:29], v2 offset:2048
	ds_read_b128 v[14:17], v2 offset:4096
	ds_read_b128 v[2:5], v2 offset:6144
	v_add_u32_e32 v7, v191, v181
	v_mfma_f32_16x16x32_bf16 v[74:77], v[176:179], v[218:221], v[74:77]
	s_mov_b32 m0, s34
	s_add_i32 s36, s36, s9
	s_add_i32 s27, s27, 1
	v_mfma_f32_16x16x32_bf16 v[70:73], v[176:179], v[222:225], v[70:73]
	v_lshl_add_u64 v[176:177], v[116:117], 0, v[100:101]
	v_lshl_add_u64 v[178:179], v[176:177], 0, s[84:85]
	v_mfma_f32_16x16x32_bf16 v[38:41], v[22:25], v[210:213], v[38:41]
	v_mfma_f32_16x16x32_bf16 v[90:93], v[22:25], v[214:217], v[90:93]
	v_mfma_f32_16x16x32_bf16 v[86:89], v[22:25], v[218:221], v[86:89]
	v_mfma_f32_16x16x32_bf16 v[94:97], v[22:25], v[222:225], v[94:97]
	ds_read_b128 v[22:25], v6
	ds_read_b128 v[18:21], v7
	v_add_u32_e32 v6, v191, v180
	ds_read_b128 v[10:13], v6
	ds_read_b128 v[6:9], v6 offset:2048
	global_load_lds_dwordx4 v[178:179], off sc1
	v_lshl_add_u64 v[178:179], v[176:177], 0, s[76:77]
	s_add_i32 m0, s34, 0x400
	v_mfma_f32_16x16x32_bf16 v[66:69], v[202:205], v[210:213], v[66:69]
	global_load_lds_dwordx4 v[178:179], off sc1
	v_lshl_add_u64 v[178:179], v[176:177], 0, s[54:55]
	s_add_i32 m0, s34, 0x800
	v_lshl_add_u64 v[176:177], v[176:177], 0, s[68:69]
	global_load_lds_dwordx4 v[178:179], off sc1
	s_add_i32 m0, s34, 0xc00
	s_mov_b64 s[34:35], 0x2300180
	global_load_lds_dwordx4 v[176:177], off sc1
	v_lshl_add_u64 v[176:177], v[118:119], 0, v[100:101]
	v_lshl_add_u64 v[178:179], v[176:177], 0, s[34:35]
	s_add_i32 m0, s36, 0x8000
	s_mov_b64 s[34:35], 0x2304180
	global_load_lds_dwordx4 v[178:179], off sc1
	v_lshl_add_u64 v[176:177], v[176:177], 0, s[34:35]
	s_add_i32 m0, s36, 0x8400
	v_mfma_f32_16x16x32_bf16 v[62:65], v[202:205], v[214:217], v[62:65]
	global_load_lds_dwordx4 v[176:177], off sc1
	v_mfma_f32_16x16x32_bf16 v[58:61], v[202:205], v[218:221], v[58:61]
	v_mfma_f32_16x16x32_bf16 v[54:57], v[202:205], v[222:225], v[54:57]
	v_mfma_f32_16x16x32_bf16 v[50:53], v[206:209], v[210:213], v[50:53]
	v_mfma_f32_16x16x32_bf16 v[46:49], v[206:209], v[214:217], v[46:49]
	v_mfma_f32_16x16x32_bf16 v[42:45], v[206:209], v[218:221], v[42:45]
	v_mfma_f32_16x16x32_bf16 v[34:37], v[206:209], v[222:225], v[34:37]
	s_add_i32 s6, s6, 1
	s_add_i32 s14, s14, 0xc000
	s_add_i32 s19, s19, 1
	v_lshl_add_u64 v[116:117], v[116:117], 0, s[2:3]
	s_cmp_eq_u32 s14, 0x9c000
	v_lshl_add_u64 v[118:119], v[118:119], 0, s[2:3]
	s_cbranch_scc0 .LBB0_84
	s_waitcnt lgkmcnt(0)
	v_mfma_f32_16x16x32_bf16 v[38:41], v[30:33], v[22:25], v[38:41]
	v_mfma_f32_16x16x32_bf16 v[90:93], v[30:33], v[18:21], v[90:93]
	v_mfma_f32_16x16x32_bf16 v[86:89], v[30:33], v[10:13], v[86:89]
	v_mfma_f32_16x16x32_bf16 v[30:33], v[30:33], v[6:9], v[94:97]
	v_mfma_f32_16x16x32_bf16 v[82:85], v[26:29], v[22:25], v[82:85]
	v_mfma_f32_16x16x32_bf16 v[78:81], v[26:29], v[18:21], v[78:81]
	v_mfma_f32_16x16x32_bf16 v[74:77], v[26:29], v[10:13], v[74:77]
	v_mfma_f32_16x16x32_bf16 v[26:29], v[26:29], v[6:9], v[70:73]
	v_mfma_f32_16x16x32_bf16 v[66:69], v[14:17], v[22:25], v[66:69]
	v_mfma_f32_16x16x32_bf16 v[62:65], v[14:17], v[18:21], v[62:65]
	v_mfma_f32_16x16x32_bf16 v[58:61], v[14:17], v[10:13], v[58:61]
	v_mfma_f32_16x16x32_bf16 v[14:17], v[14:17], v[6:9], v[54:57]
	v_mfma_f32_16x16x32_bf16 v[22:25], v[2:5], v[22:25], v[50:53]
	v_mfma_f32_16x16x32_bf16 v[18:21], v[2:5], v[18:21], v[46:49]
	s_nop 2
	ds_read_b128 v[46:49], v163
	ds_read_b128 v[50:53], v164 offset:2048
	ds_read_b128 v[54:57], v164 offset:4096
	ds_read_b128 v[70:73], v164 offset:6144
	v_mfma_f32_16x16x32_bf16 v[10:13], v[2:5], v[10:13], v[42:45]
	s_nop 2
	ds_read_b128 v[42:45], v165 offset:32768
	ds_read_b128 v[94:97], v166 offset:34816
	ds_read_b128 v[116:119], v166 offset:36864
	ds_read_b128 v[176:179], v166 offset:38912
	v_mfma_f32_16x16x32_bf16 v[2:5], v[2:5], v[6:9], v[34:37]
	s_waitcnt lgkmcnt(0)
	v_mfma_f32_16x16x32_bf16 v[6:9], v[46:49], v[42:45], v[38:41]
	s_waitcnt vmcnt(6)
	s_waitcnt lgkmcnt(0)
	s_barrier
	v_mfma_f32_16x16x32_bf16 v[34:37], v[46:49], v[94:97], v[90:93]
	v_mfma_f32_16x16x32_bf16 v[38:41], v[46:49], v[116:119], v[86:89]
	s_nop 1
	v_add_u32_e32 v90, 0x20800, v161
	v_mfma_f32_16x16x32_bf16 v[30:33], v[46:49], v[176:179], v[30:33]
	v_mfma_f32_16x16x32_bf16 v[46:49], v[50:53], v[42:45], v[82:85]
	v_mfma_f32_16x16x32_bf16 v[78:81], v[50:53], v[94:97], v[78:81]
	v_mfma_f32_16x16x32_bf16 v[74:77], v[50:53], v[116:119], v[74:77]
	v_mfma_f32_16x16x32_bf16 v[26:29], v[50:53], v[176:179], v[26:29]
	v_mfma_f32_16x16x32_bf16 v[50:53], v[54:57], v[42:45], v[66:69]
	v_mfma_f32_16x16x32_bf16 v[62:65], v[54:57], v[94:97], v[62:65]
	v_mfma_f32_16x16x32_bf16 v[58:61], v[54:57], v[116:119], v[58:61]
	v_mfma_f32_16x16x32_bf16 v[14:17], v[54:57], v[176:179], v[14:17]
	v_add_u32_e32 v54, v126, v120
	ds_read_b128 v[54:57], v54
	ds_read_b128 v[66:69], v167 offset:2048
	v_mfma_f32_16x16x32_bf16 v[18:21], v[70:73], v[94:97], v[18:21]
	v_add_u32_e32 v94, 0x21000, v161
	v_mfma_f32_16x16x32_bf16 v[10:13], v[70:73], v[116:119], v[10:13]
	v_add_u32_e32 v116, 0x21800, v161
	v_mfma_f32_16x16x32_bf16 v[22:25], v[70:73], v[42:45], v[22:25]
	ds_read_b128 v[42:45], v167 offset:4096
	ds_read_b128 v[82:85], v167 offset:6144
	ds_read_b128 v[86:89], v168
	ds_read_b128 v[90:93], v90
	ds_read_b128 v[94:97], v94
	ds_read_b128 v[116:119], v116
	v_mfma_f32_16x16x32_bf16 v[2:5], v[70:73], v[176:179], v[2:5]
	s_waitcnt lgkmcnt(0)
	v_mfma_f32_16x16x32_bf16 v[50:53], v[42:45], v[86:89], v[50:53]
	v_mfma_f32_16x16x32_bf16 v[62:65], v[42:45], v[90:93], v[62:65]
	v_mfma_f32_16x16x32_bf16 v[58:61], v[42:45], v[94:97], v[58:61]
	v_mfma_f32_16x16x32_bf16 v[14:17], v[42:45], v[116:119], v[14:17]
	v_add_u32_e32 v42, v126, v124
	v_mfma_f32_16x16x32_bf16 v[6:9], v[54:57], v[86:89], v[6:9]
	v_mfma_f32_16x16x32_bf16 v[34:37], v[54:57], v[90:93], v[34:37]
	v_mfma_f32_16x16x32_bf16 v[38:41], v[54:57], v[94:97], v[38:41]
	v_mfma_f32_16x16x32_bf16 v[30:33], v[54:57], v[116:119], v[30:33]
	v_mfma_f32_16x16x32_bf16 v[46:49], v[66:69], v[86:89], v[46:49]
	v_mfma_f32_16x16x32_bf16 v[54:57], v[66:69], v[90:93], v[78:81]
	v_mfma_f32_16x16x32_bf16 v[70:73], v[66:69], v[94:97], v[74:77]
	v_mfma_f32_16x16x32_bf16 v[26:29], v[66:69], v[116:119], v[26:29]
	ds_read_b128 v[42:45], v42
	ds_read_b128 v[66:69], v169
	ds_read_b128 v[74:77], v170
	ds_read_b128 v[78:81], v171
	v_mfma_f32_16x16x32_bf16 v[22:25], v[82:85], v[86:89], v[22:25]
	v_mfma_f32_16x16x32_bf16 v[18:21], v[82:85], v[90:93], v[18:21]
	v_mfma_f32_16x16x32_bf16 v[10:13], v[82:85], v[94:97], v[10:13]
	ds_read_b128 v[86:89], v172
	ds_read_b128 v[90:93], v173
	ds_read_b128 v[94:97], v174
	ds_read_b128 v[176:179], v175
	v_mfma_f32_16x16x32_bf16 v[2:5], v[82:85], v[116:119], v[2:5]
	s_waitcnt vmcnt(0)
	s_waitcnt lgkmcnt(0)
	v_mfma_f32_16x16x32_bf16 v[6:9], v[42:45], v[86:89], v[6:9]
	s_waitcnt lgkmcnt(0)
	s_barrier
	v_mfma_f32_16x16x32_bf16 v[34:37], v[42:45], v[90:93], v[34:37]
	v_mfma_f32_16x16x32_bf16 v[38:41], v[42:45], v[94:97], v[38:41]
	v_mfma_f32_16x16x32_bf16 v[30:33], v[42:45], v[176:179], v[30:33]
	v_mfma_f32_16x16x32_bf16 v[42:45], v[66:69], v[86:89], v[46:49]
	v_mfma_f32_16x16x32_bf16 v[46:49], v[66:69], v[90:93], v[54:57]
	v_mfma_f32_16x16x32_bf16 v[54:57], v[66:69], v[94:97], v[70:73]
	v_mfma_f32_16x16x32_bf16 v[26:29], v[66:69], v[176:179], v[26:29]
	v_mfma_f32_16x16x32_bf16 v[50:53], v[74:77], v[86:89], v[50:53]
	v_mfma_f32_16x16x32_bf16 v[62:65], v[74:77], v[90:93], v[62:65]
	v_mfma_f32_16x16x32_bf16 v[58:61], v[74:77], v[94:97], v[58:61]
	v_mfma_f32_16x16x32_bf16 v[14:17], v[74:77], v[176:179], v[14:17]
	ds_read_b128 v[66:69], v161 offset:38912
	ds_read_b128 v[70:73], v161 offset:36864
	ds_read_b128 v[74:77], v161 offset:34816
	ds_read_b128 v[82:85], v135 offset:32768
	v_mfma_f32_16x16x32_bf16 v[22:25], v[78:81], v[86:89], v[22:25]
	v_mfma_f32_16x16x32_bf16 v[18:21], v[78:81], v[90:93], v[18:21]
	v_mfma_f32_16x16x32_bf16 v[10:13], v[78:81], v[94:97], v[10:13]
	ds_read_b128 v[86:89], v134 offset:6144
	ds_read_b128 v[90:93], v134 offset:4096
	ds_read_b128 v[94:97], v134 offset:2048
	ds_read_b128 v[116:119], v133
	v_mfma_f32_16x16x32_bf16 v[2:5], v[78:81], v[176:179], v[2:5]
	s_waitcnt lgkmcnt(0)
	v_mfma_f32_16x16x32_bf16 v[78:81], v[94:97], v[74:77], v[46:49]
	s_nop 2
	v_add_u32_e32 v46, v105, v124
	v_mfma_f32_16x16x32_bf16 v[6:9], v[116:119], v[82:85], v[6:9]
	v_add_u32_e32 v47, v121, v124
	v_mfma_f32_16x16x32_bf16 v[34:37], v[116:119], v[74:77], v[34:37]
	v_mfma_f32_16x16x32_bf16 v[38:41], v[116:119], v[70:73], v[38:41]
	v_mfma_f32_16x16x32_bf16 v[30:33], v[116:119], v[66:69], v[30:33]
	v_mfma_f32_16x16x32_bf16 v[42:45], v[94:97], v[82:85], v[42:45]
	v_mfma_f32_16x16x32_bf16 v[116:119], v[94:97], v[70:73], v[54:57]
	v_mfma_f32_16x16x32_bf16 v[26:29], v[94:97], v[66:69], v[26:29]
	v_mfma_f32_16x16x32_bf16 v[94:97], v[90:93], v[82:85], v[50:53]
	v_mfma_f32_16x16x32_bf16 v[176:179], v[90:93], v[74:77], v[62:65]
	v_mfma_f32_16x16x32_bf16 v[202:205], v[90:93], v[70:73], v[58:61]
	v_mfma_f32_16x16x32_bf16 v[14:17], v[90:93], v[66:69], v[14:17]
	v_mfma_f32_16x16x32_bf16 v[82:85], v[86:89], v[82:85], v[22:25]
	s_nop 2
	ds_read_b128 v[22:25], v46
	ds_read_b128 v[90:93], v47 offset:2048
	v_add_u32_e32 v46, v122, v124
	v_mfma_f32_16x16x32_bf16 v[74:77], v[86:89], v[74:77], v[18:21]
	s_nop 2
	ds_read_b128 v[18:21], v47 offset:4096
	ds_read_b128 v[206:209], v47 offset:6144
	v_add_u32_e32 v47, v123, v124
	v_mfma_f32_16x16x32_bf16 v[70:73], v[86:89], v[70:73], v[10:13]
	s_nop 2
	ds_read_b128 v[10:13], v46 offset:32768
	ds_read_b128 v[210:213], v47 offset:34816
	ds_read_b128 v[214:217], v47 offset:36864
	ds_read_b128 v[218:221], v47 offset:38912
	v_mfma_f32_16x16x32_bf16 v[2:5], v[86:89], v[66:69], v[2:5]
	s_waitcnt lgkmcnt(0)
	v_mfma_f32_16x16x32_bf16 v[62:65], v[22:25], v[10:13], v[6:9]
	s_waitcnt vmcnt(0)
	s_waitcnt lgkmcnt(0)
	s_barrier
	v_mfma_f32_16x16x32_bf16 v[58:61], v[22:25], v[210:213], v[34:37]
	v_mfma_f32_16x16x32_bf16 v[54:57], v[22:25], v[214:217], v[38:41]
	v_mfma_f32_16x16x32_bf16 v[50:53], v[22:25], v[218:221], v[30:33]
	v_mfma_f32_16x16x32_bf16 v[46:49], v[90:93], v[10:13], v[42:45]
	v_mfma_f32_16x16x32_bf16 v[42:45], v[90:93], v[210:213], v[78:81]
	v_mfma_f32_16x16x32_bf16 v[38:41], v[90:93], v[214:217], v[116:119]
	v_mfma_f32_16x16x32_bf16 v[34:37], v[90:93], v[218:221], v[26:29]
	v_mfma_f32_16x16x32_bf16 v[30:33], v[18:21], v[10:13], v[94:97]
	v_mfma_f32_16x16x32_bf16 v[26:29], v[18:21], v[210:213], v[176:179]
	v_mfma_f32_16x16x32_bf16 v[22:25], v[18:21], v[214:217], v[202:205]
	v_mfma_f32_16x16x32_bf16 v[18:21], v[18:21], v[218:221], v[14:17]
	v_mfma_f32_16x16x32_bf16 v[14:17], v[206:209], v[10:13], v[82:85]
	v_mfma_f32_16x16x32_bf16 v[10:13], v[206:209], v[210:213], v[74:77]
	v_mfma_f32_16x16x32_bf16 v[6:9], v[206:209], v[214:217], v[70:73]
	v_mfma_f32_16x16x32_bf16 v[2:5], v[206:209], v[218:221], v[2:5]
	s_waitcnt lgkmcnt(0)
	s_barrier
	s_load_dword s6, s[78:79], 0x0
	s_waitcnt lgkmcnt(0)
	s_add_i32 s49, s6, s49
	s_cmpk_gt_i32 s49, 0x2ff
	s_cselect_b64 s[34:35], -1, 0
	s_cmpk_lt_i32 s49, 0x300
	s_cbranch_scc0 .LBB0_80
	s_mul_hi_i32 s6, s49, 0x2aaaaaab
	s_lshr_b32 s14, s6, 31
	s_ashr_i32 s6, s6, 2
	s_add_i32 s6, s6, s14
	s_mul_i32 s14, s6, 24
	s_sub_i32 s14, s49, s14
	v_readlane_b32 s52, v255, 40
	s_add_i32 s52, s52, 0x5d0e1000
	s_lshl_b32 s53, s14, 7
	s_add_u32 s64, s94, 0xcbc8000
	s_addc_u32 s65, s95, 0
	v_and_b32_e32 v226, 7, v137
	v_lshlrev_b32_e32 v226, 4, v226
	v_add_u32_e32 v226, s53, v226
	s_mov_b32 s53, 0x100000

.Lm1ok_b:
	v_lshl_add_u32 v66, s14, 8, v98
	v_ashrrev_i32_e32 v67, 31, v66
	v_lshlrev_b64 v[66:67], 11, v[66:67]
	s_mov_b32 m0, s8
	v_lshl_add_u64 v[66:67], v[108:109], 0, v[66:67]
	v_lshl_add_u32 v68, s6, 7, v104
	global_load_lds_dwordx4 v[66:67], off sc1
	v_lshl_add_u64 v[70:71], v[66:67], 0, s[30:31]
	s_mov_b32 m0, s11
	v_ashrrev_i32_e32 v69, 31, v68
	global_load_lds_dwordx4 v[70:71], off sc1
	v_lshl_add_u64 v[70:71], v[66:67], 0, s[24:25]
	s_add_i32 m0, s8, 0x800
	s_mov_b64 s[16:17], 0xc000
	v_lshlrev_b64 v[68:69], 11, v[68:69]
	global_load_lds_dwordx4 v[70:71], off sc1
	v_lshl_add_u64 v[70:71], v[66:67], 0, s[16:17]
	s_mov_b32 m0, s12
	v_lshl_add_u64 v[68:69], v[110:111], 0, v[68:69]
	global_load_lds_dwordx4 v[70:71], off sc1
	s_mov_b32 m0, s13
	v_lshl_add_u64 v[70:71], v[68:69], 0, s[30:31]
	global_load_lds_dwordx4 v[68:69], off sc1
	s_mov_b32 m0, s40
	s_mov_b64 s[16:17], 0x4080
	global_load_lds_dwordx4 v[70:71], off sc1
	v_lshl_add_u64 v[70:71], v[66:67], 0, s[2:3]
	s_add_i32 m0, s8, 0xc000
	s_mov_b64 s[36:37], 0x8080
	global_load_lds_dwordx4 v[70:71], off sc1
	v_lshl_add_u64 v[70:71], v[66:67], 0, s[16:17]
	s_mov_b32 m0, s41
	s_mov_b64 s[38:39], 0x8100
	global_load_lds_dwordx4 v[70:71], off sc1
	v_lshl_add_u64 v[70:71], v[66:67], 0, s[36:37]
	s_mov_b32 m0, s42
	s_mov_b64 s[36:37], 0xc080
	global_load_lds_dwordx4 v[70:71], off sc1
	v_lshl_add_u64 v[70:71], v[66:67], 0, s[36:37]
	s_mov_b32 m0, s43
	s_mov_b64 s[36:37], 0x4100
	global_load_lds_dwordx4 v[70:71], off sc1
	v_lshl_add_u64 v[70:71], v[68:69], 0, s[2:3]
	s_add_i32 m0, s9, 0x14000
	s_nop 0
	global_load_lds_dwordx4 v[70:71], off sc1
	v_lshl_add_u64 v[70:71], v[68:69], 0, s[16:17]
	s_mov_b32 m0, s44
	s_mov_b64 s[16:17], 0x100
	global_load_lds_dwordx4 v[70:71], off sc1
	s_branch .LBB0_80

.Lln1_pok1:
	v_add_f32_e32 v250, v250, v226
	v_add_f32_e32 v252, v252, v228
	v_add_f32_e32 v250, v250, v230
	v_add_f32_e32 v252, v252, v232
	v_add_f32_e32 v250, v250, v234
	v_add_f32_e32 v252, v252, v236
	v_add_f32_e32 v250, v250, v238
	v_add_f32_e32 v252, v252, v240
	v_add_f32_e32 v250, v250, v206
	v_add_f32_e32 v252, v252, v208
	v_add_f32_e32 v250, v250, v210
	v_add_f32_e32 v252, v252, v212
	v_add_f32_e32 v250, v250, v214
	v_add_f32_e32 v252, v252, v216
	v_add_f32_e32 v250, v250, v218
	v_add_f32_e32 v252, v252, v220
	global_load_dwordx4 v[226:229], v246, s[22:23]
	global_load_dwordx4 v[230:233], v246, s[22:23] offset:64
	global_load_dwordx4 v[234:237], v246, s[22:23] offset:128
	global_load_dwordx4 v[238:241], v246, s[22:23] offset:192
	v_mov_b32_e32 v206, v250
	v_mov_b32_e32 v207, v252
	v_mul_f32_e32 v208, 0x3a800000, v206
	v_mul_f32_e32 v209, v208, v208
	v_mov_b32_e32 v216, 0x3a800000
	v_fma_f32 v209, v207, v216, -v209
	v_max_f32_e32 v209, 0, v209
	v_add_f32_e32 v209, 0x3727c5ac, v209
	v_rsq_f32_e32 v209, v209
	v_mov_b32_e32 v210, v208
	v_mov_b32_e32 v211, v208
	v_mov_b32_e32 v214, v209
	v_mov_b32_e32 v215, v209
	s_nop 1
	v_permlane16_swap_b32_e32 v210, v211
	v_permlane16_swap_b32_e32 v214, v215
	v_mov_b32_e32 v212, v210
	v_mov_b32_e32 v213, v211
	v_mov_b32_e32 v216, v214
	v_mov_b32_e32 v217, v215
	s_nop 1
	v_permlane32_swap_b32_e32 v210, v212
	v_permlane32_swap_b32_e32 v211, v213
	v_permlane32_swap_b32_e32 v214, v216
	v_permlane32_swap_b32_e32 v215, v217
	v_readfirstlane_b32 s64, v137
	s_lshr_b32 s64, s64, 6
	s_lshl_b32 s64, s64, 14
	v_and_b32_e32 v222, 63, v137
	v_and_b32_e32 v246, 15, v222
	v_lshrrev_b32_e32 v247, 4, v222
	v_and_b32_e32 v248, 3, v246
	v_xor_b32_e32 v248, v248, v247
	v_lshlrev_b32_e32 v248, 4, v248
	v_lshl_add_u32 v248, v246, 8, v248
	v_add_u32_e32 v248, s64, v248
	v_lshl_add_u32 v249, v222, 4, s64
	v_add_u32_e32 v250, s36, v247
	v_lshlrev_b32_e32 v250, 12, v250
	v_xor_b32_e32 v251, v246, v247
	v_lshl_add_u32 v250, v251, 4, v250
	s_lshl_b32 s65, s37, 2
	v_add_u32_e32 v250, s65, v250
	v_sub_f32_e32 v62, v62, v210
	v_sub_f32_e32 v63, v63, v210
	v_sub_f32_e32 v64, v64, v210
	v_sub_f32_e32 v65, v65, v210
	v_mul_f32_e32 v62, v214, v62
	v_mul_f32_e32 v63, v214, v63
	v_mul_f32_e32 v64, v214, v64
	v_mul_f32_e32 v65, v214, v65
	v_fma_f32 v62, v66, v62, v90
	v_fma_f32 v63, v67, v63, v91
	v_fma_f32 v64, v68, v64, v92
	v_fma_f32 v65, v69, v65, v93
	ds_write_b128 v248, v[62:65] offset:0
	v_sub_f32_e32 v86, v86, v210
	v_sub_f32_e32 v87, v87, v210
	v_sub_f32_e32 v88, v88, v210
	v_sub_f32_e32 v89, v89, v210
	v_mul_f32_e32 v86, v214, v86
	v_mul_f32_e32 v87, v214, v87
	v_mul_f32_e32 v88, v214, v88
	v_mul_f32_e32 v89, v214, v89
	v_fma_f32 v86, v74, v86, v94
	v_fma_f32 v87, v75, v87, v95
	v_fma_f32 v88, v76, v88, v96
	v_fma_f32 v89, v77, v89, v97
	ds_write_b128 v248, v[86:89] offset:64
	v_sub_f32_e32 v70, v70, v210
	v_sub_f32_e32 v71, v71, v210
	v_sub_f32_e32 v72, v72, v210
	v_sub_f32_e32 v73, v73, v210
	v_mul_f32_e32 v70, v214, v70
	v_mul_f32_e32 v71, v214, v71
	v_mul_f32_e32 v72, v214, v72
	v_mul_f32_e32 v73, v214, v73
	v_fma_f32 v70, v78, v70, v108
	v_fma_f32 v71, v79, v71, v109
	v_fma_f32 v72, v80, v72, v110
	v_fma_f32 v73, v81, v73, v111
	ds_write_b128 v248, v[70:73] offset:128
	v_sub_f32_e32 v176, v176, v210
	v_sub_f32_e32 v177, v177, v210
	v_sub_f32_e32 v178, v178, v210
	v_sub_f32_e32 v179, v179, v210
	v_mul_f32_e32 v176, v214, v176
	v_mul_f32_e32 v177, v214, v177
	v_mul_f32_e32 v178, v214, v178
	v_mul_f32_e32 v179, v214, v179
	v_fma_f32 v176, v82, v176, v172
	v_fma_f32 v177, v83, v177, v173
	v_fma_f32 v178, v84, v178, v174
	v_fma_f32 v179, v85, v179, v175
	ds_write_b128 v248, v[176:179] offset:192
	v_sub_f32_e32 v202, v202, v211
	v_sub_f32_e32 v203, v203, v211
	v_sub_f32_e32 v204, v204, v211
	v_sub_f32_e32 v205, v205, v211
	v_mul_f32_e32 v202, v215, v202
	v_mul_f32_e32 v203, v215, v203
	v_mul_f32_e32 v204, v215, v204
	v_mul_f32_e32 v205, v215, v205
	v_fma_f32 v202, v66, v202, v90
	v_fma_f32 v203, v67, v203, v91
	v_fma_f32 v204, v68, v204, v92
	v_fma_f32 v205, v69, v205, v93
	ds_write_b128 v248, v[202:205] offset:4096
	v_sub_f32_e32 v54, v54, v211
	v_sub_f32_e32 v55, v55, v211
	v_sub_f32_e32 v56, v56, v211
	v_sub_f32_e32 v57, v57, v211
	v_mul_f32_e32 v54, v215, v54
	v_mul_f32_e32 v55, v215, v55
	v_mul_f32_e32 v56, v215, v56
	v_mul_f32_e32 v57, v215, v57
	v_fma_f32 v54, v74, v54, v94
	v_fma_f32 v55, v75, v55, v95
	v_fma_f32 v56, v76, v56, v96
	v_fma_f32 v57, v77, v57, v97
	ds_write_b128 v248, v[54:57] offset:4160
	v_sub_f32_e32 v58, v58, v211
	v_sub_f32_e32 v59, v59, v211
	v_sub_f32_e32 v60, v60, v211
	v_sub_f32_e32 v61, v61, v211
	v_mul_f32_e32 v58, v215, v58
	v_mul_f32_e32 v59, v215, v59
	v_mul_f32_e32 v60, v215, v60
	v_mul_f32_e32 v61, v215, v61
	v_fma_f32 v58, v78, v58, v108
	v_fma_f32 v59, v79, v59, v109
	v_fma_f32 v60, v80, v60, v110
	v_fma_f32 v61, v81, v61, v111
	ds_write_b128 v248, v[58:61] offset:4224
	v_sub_f32_e32 v34, v34, v211
	v_sub_f32_e32 v35, v35, v211
	v_sub_f32_e32 v36, v36, v211
	v_sub_f32_e32 v37, v37, v211
	v_mul_f32_e32 v34, v215, v34
	v_mul_f32_e32 v35, v215, v35
	v_mul_f32_e32 v36, v215, v36
	v_mul_f32_e32 v37, v215, v37
	v_fma_f32 v34, v82, v34, v172
	v_fma_f32 v35, v83, v35, v173
	v_fma_f32 v36, v84, v36, v174
	v_fma_f32 v37, v85, v37, v175
	ds_write_b128 v248, v[34:37] offset:4288
	v_sub_f32_e32 v30, v30, v212
	v_sub_f32_e32 v31, v31, v212
	v_sub_f32_e32 v32, v32, v212
	v_sub_f32_e32 v33, v33, v212
	v_mul_f32_e32 v30, v216, v30
	v_mul_f32_e32 v31, v216, v31
	v_mul_f32_e32 v32, v216, v32
	v_mul_f32_e32 v33, v216, v33
	v_fma_f32 v30, v66, v30, v90
	v_fma_f32 v31, v67, v31, v91
	v_fma_f32 v32, v68, v32, v92
	v_fma_f32 v33, v69, v33, v93
	ds_write_b128 v248, v[30:33] offset:8192
	v_sub_f32_e32 v26, v26, v212
	v_sub_f32_e32 v27, v27, v212
	v_sub_f32_e32 v28, v28, v212
	v_sub_f32_e32 v29, v29, v212
	v_mul_f32_e32 v26, v216, v26
	v_mul_f32_e32 v27, v216, v27
	v_mul_f32_e32 v28, v216, v28
	v_mul_f32_e32 v29, v216, v29
	v_fma_f32 v26, v74, v26, v94
	v_fma_f32 v27, v75, v27, v95
	v_fma_f32 v28, v76, v28, v96
	v_fma_f32 v29, v77, v29, v97
	ds_write_b128 v248, v[26:29] offset:8256
	v_sub_f32_e32 v22, v22, v212
	v_sub_f32_e32 v23, v23, v212
	v_sub_f32_e32 v24, v24, v212
	v_sub_f32_e32 v25, v25, v212
	v_mul_f32_e32 v22, v216, v22
	v_mul_f32_e32 v23, v216, v23
	v_mul_f32_e32 v24, v216, v24
	v_mul_f32_e32 v25, v216, v25
	v_fma_f32 v22, v78, v22, v108
	v_fma_f32 v23, v79, v23, v109
	v_fma_f32 v24, v80, v24, v110
	v_fma_f32 v25, v81, v25, v111
	ds_write_b128 v248, v[22:25] offset:8320
	v_sub_f32_e32 v18, v18, v212
	v_sub_f32_e32 v19, v19, v212
	v_sub_f32_e32 v20, v20, v212
	v_sub_f32_e32 v21, v21, v212
	v_mul_f32_e32 v18, v216, v18
	v_mul_f32_e32 v19, v216, v19
	v_mul_f32_e32 v20, v216, v20
	v_mul_f32_e32 v21, v216, v21
	v_fma_f32 v18, v82, v18, v172
	v_fma_f32 v19, v83, v19, v173
	v_fma_f32 v20, v84, v20, v174
	v_fma_f32 v21, v85, v21, v175
	ds_write_b128 v248, v[18:21] offset:8384
	v_sub_f32_e32 v14, v14, v213
	v_sub_f32_e32 v15, v15, v213
	v_sub_f32_e32 v16, v16, v213
	v_sub_f32_e32 v17, v17, v213
	v_mul_f32_e32 v14, v217, v14
	v_mul_f32_e32 v15, v217, v15
	v_mul_f32_e32 v16, v217, v16
	v_mul_f32_e32 v17, v217, v17
	v_fma_f32 v14, v66, v14, v90
	v_fma_f32 v15, v67, v15, v91
	v_fma_f32 v16, v68, v16, v92
	v_fma_f32 v17, v69, v17, v93
	ds_write_b128 v248, v[14:17] offset:12288
	v_sub_f32_e32 v10, v10, v213
	v_sub_f32_e32 v11, v11, v213
	v_sub_f32_e32 v12, v12, v213
	v_sub_f32_e32 v13, v13, v213
	v_mul_f32_e32 v10, v217, v10
	v_mul_f32_e32 v11, v217, v11
	v_mul_f32_e32 v12, v217, v12
	v_mul_f32_e32 v13, v217, v13
	v_fma_f32 v10, v74, v10, v94
	v_fma_f32 v11, v75, v11, v95
	v_fma_f32 v12, v76, v12, v96
	v_fma_f32 v13, v77, v13, v97
	ds_write_b128 v248, v[10:13] offset:12352
	v_sub_f32_e32 v6, v6, v213
	v_sub_f32_e32 v7, v7, v213
	v_sub_f32_e32 v8, v8, v213
	v_sub_f32_e32 v9, v9, v213
	v_mul_f32_e32 v6, v217, v6
	v_mul_f32_e32 v7, v217, v7
	v_mul_f32_e32 v8, v217, v8
	v_mul_f32_e32 v9, v217, v9
	v_fma_f32 v6, v78, v6, v108
	v_fma_f32 v7, v79, v7, v109
	v_fma_f32 v8, v80, v8, v110
	v_fma_f32 v9, v81, v9, v111
	ds_write_b128 v248, v[6:9] offset:12416
	v_sub_f32_e32 v2, v2, v213
	v_sub_f32_e32 v3, v3, v213
	v_sub_f32_e32 v4, v4, v213
	v_sub_f32_e32 v5, v5, v213
	v_mul_f32_e32 v2, v217, v2
	v_mul_f32_e32 v3, v217, v3
	v_mul_f32_e32 v4, v217, v4
	v_mul_f32_e32 v5, v217, v5
	v_fma_f32 v2, v82, v2, v172
	v_fma_f32 v3, v83, v3, v173
	v_fma_f32 v4, v84, v4, v174
	v_fma_f32 v5, v85, v5, v175
	ds_write_b128 v248, v[2:5] offset:12480
	s_waitcnt lgkmcnt(0)
	ds_read_b128 v[66:69], v249 offset:0
	ds_read_b128 v[74:77], v249 offset:1024
	ds_read_b128 v[78:81], v249 offset:2048
	ds_read_b128 v[82:85], v249 offset:3072
	ds_read_b128 v[90:93], v249 offset:4096
	ds_read_b128 v[94:97], v249 offset:5120
	ds_read_b128 v[108:111], v249 offset:6144
	ds_read_b128 v[172:175], v249 offset:7168
	s_waitcnt lgkmcnt(7)
	global_store_dwordx4 v250, v[66:69], s[26:27] sc1
	s_waitcnt lgkmcnt(6)
	v_add_u32_e32 v251, 0x4000, v250
	global_store_dwordx4 v251, v[74:77], s[26:27] sc1
	s_waitcnt lgkmcnt(5)
	v_add_u32_e32 v251, 0x8000, v250
	global_store_dwordx4 v251, v[78:81], s[26:27] sc1
	s_waitcnt lgkmcnt(4)
	v_add_u32_e32 v251, 0xc000, v250
	global_store_dwordx4 v251, v[82:85], s[26:27] sc1
	s_waitcnt lgkmcnt(3)
	v_add_u32_e32 v251, 0x10000, v250
	global_store_dwordx4 v251, v[90:93], s[26:27] sc1
	s_waitcnt lgkmcnt(2)
	v_add_u32_e32 v251, 0x14000, v250
	global_store_dwordx4 v251, v[94:97], s[26:27] sc1
	s_waitcnt lgkmcnt(1)
	v_add_u32_e32 v251, 0x18000, v250
	global_store_dwordx4 v251, v[108:111], s[26:27] sc1
	s_waitcnt lgkmcnt(0)
	v_add_u32_e32 v251, 0x1c000, v250
	global_store_dwordx4 v251, v[172:175], s[26:27] sc1
	s_nop 1
	ds_read_b128 v[66:69], v249 offset:8192
	ds_read_b128 v[74:77], v249 offset:9216
	ds_read_b128 v[78:81], v249 offset:10240
	ds_read_b128 v[82:85], v249 offset:11264
	ds_read_b128 v[90:93], v249 offset:12288
	ds_read_b128 v[94:97], v249 offset:13312
	ds_read_b128 v[108:111], v249 offset:14336
	ds_read_b128 v[172:175], v249 offset:15360
	s_waitcnt lgkmcnt(7)
	v_add_u32_e32 v251, 0x20000, v250
	global_store_dwordx4 v251, v[66:69], s[26:27] sc1
	s_waitcnt lgkmcnt(6)
	v_add_u32_e32 v251, 0x24000, v250
	global_store_dwordx4 v251, v[74:77], s[26:27] sc1
	s_waitcnt lgkmcnt(5)
	v_add_u32_e32 v251, 0x28000, v250
	global_store_dwordx4 v251, v[78:81], s[26:27] sc1
	s_waitcnt lgkmcnt(4)
	v_add_u32_e32 v251, 0x2c000, v250
	global_store_dwordx4 v251, v[82:85], s[26:27] sc1
	s_waitcnt lgkmcnt(3)
	v_add_u32_e32 v251, 0x30000, v250
	global_store_dwordx4 v251, v[90:93], s[26:27] sc1
	s_waitcnt lgkmcnt(2)
	v_add_u32_e32 v251, 0x34000, v250
	global_store_dwordx4 v251, v[94:97], s[26:27] sc1
	s_waitcnt lgkmcnt(1)
	v_add_u32_e32 v251, 0x38000, v250
	global_store_dwordx4 v251, v[108:111], s[26:27] sc1
	s_waitcnt lgkmcnt(0)
	v_add_u32_e32 v251, 0x3c000, v250
	global_store_dwordx4 v251, v[172:175], s[26:27] sc1
	s_nop 1
	s_add_u32 s44, s94, 0x7b48000
	s_addc_u32 s45, s95, 0
	s_waitcnt vmcnt(16)
	v_add_f32_e32 v226, 1.0, v226
	v_add_f32_e32 v227, 1.0, v227
	v_add_f32_e32 v228, 1.0, v228
	v_add_f32_e32 v229, 1.0, v229
	v_add_f32_e32 v230, 1.0, v230
	v_add_f32_e32 v231, 1.0, v231
	v_add_f32_e32 v232, 1.0, v232
	v_add_f32_e32 v233, 1.0, v233
	v_add_f32_e32 v234, 1.0, v234
	v_add_f32_e32 v235, 1.0, v235
	v_add_f32_e32 v236, 1.0, v236
	v_add_f32_e32 v237, 1.0, v237
	v_add_f32_e32 v238, 1.0, v238
	v_add_f32_e32 v239, 1.0, v239
	v_add_f32_e32 v240, 1.0, v240
	v_add_f32_e32 v241, 1.0, v241
	v_and_b32_e32 v251, 7, v246
	v_lshlrev_b32_e32 v251, 1, v251
	v_or_b32_e32 v218, 0, v247
	v_xor_b32_e32 v218, v218, v251
	v_lshlrev_b32_e32 v218, 3, v218
	v_lshl_add_u32 v218, v246, 7, v218
	v_add_u32_e32 v218, s64, v218
	v_or_b32_e32 v219, 4, v247
	v_xor_b32_e32 v219, v219, v251
	v_lshlrev_b32_e32 v219, 3, v219
	v_lshl_add_u32 v219, v246, 7, v219
	v_add_u32_e32 v219, s64, v219
	v_or_b32_e32 v220, 8, v247
	v_xor_b32_e32 v220, v220, v251
	v_lshlrev_b32_e32 v220, 3, v220
	v_lshl_add_u32 v220, v246, 7, v220
	v_add_u32_e32 v220, s64, v220
	v_or_b32_e32 v221, 12, v247
	v_xor_b32_e32 v221, v221, v251
	v_lshlrev_b32_e32 v221, 3, v221
	v_lshl_add_u32 v221, v246, 7, v221
	v_add_u32_e32 v221, s64, v221
	v_lshrrev_b32_e32 v248, 3, v222
	v_and_b32_e32 v251, 7, v222
	v_xor_b32_e32 v251, v251, v248
	v_add_u32_e32 v248, s36, v248
	v_lshlrev_b32_e32 v248, 11, v248
	v_lshl_add_u32 v248, v251, 4, v248
	s_lshl_b32 s65, s37, 1
	v_add_u32_e32 v248, s65, v248
	v_fma_f32 v62, v226, v62, v38
	v_fma_f32 v63, v227, v63, v39
	v_fma_f32 v64, v228, v64, v40
	v_fma_f32 v65, v229, v65, v41
	v_cvt_pk_bf16_f32 v62, v62, v63
	v_cvt_pk_bf16_f32 v63, v64, v65
	ds_write_b64 v218, v[62:63] offset:0
	v_fma_f32 v86, v230, v86, v42
	v_fma_f32 v87, v231, v87, v43
	v_fma_f32 v88, v232, v88, v44
	v_fma_f32 v89, v233, v89, v45
	v_cvt_pk_bf16_f32 v86, v86, v87
	v_cvt_pk_bf16_f32 v87, v88, v89
	ds_write_b64 v219, v[86:87] offset:0
	v_fma_f32 v70, v234, v70, v46
	v_fma_f32 v71, v235, v71, v47
	v_fma_f32 v72, v236, v72, v48
	v_fma_f32 v73, v237, v73, v49
	v_cvt_pk_bf16_f32 v70, v70, v71
	v_cvt_pk_bf16_f32 v71, v72, v73
	ds_write_b64 v220, v[70:71] offset:0
	v_fma_f32 v176, v238, v176, v50
	v_fma_f32 v177, v239, v177, v51
	v_fma_f32 v178, v240, v178, v52
	v_fma_f32 v179, v241, v179, v53
	v_cvt_pk_bf16_f32 v176, v176, v177
	v_cvt_pk_bf16_f32 v177, v178, v179
	ds_write_b64 v221, v[176:177] offset:0
	v_fma_f32 v202, v226, v202, v38
	v_fma_f32 v203, v227, v203, v39
	v_fma_f32 v204, v228, v204, v40
	v_fma_f32 v205, v229, v205, v41
	v_cvt_pk_bf16_f32 v202, v202, v203
	v_cvt_pk_bf16_f32 v203, v204, v205
	ds_write_b64 v218, v[202:203] offset:2048
	v_fma_f32 v54, v230, v54, v42
	v_fma_f32 v55, v231, v55, v43
	v_fma_f32 v56, v232, v56, v44
	v_fma_f32 v57, v233, v57, v45
	v_cvt_pk_bf16_f32 v54, v54, v55
	v_cvt_pk_bf16_f32 v55, v56, v57
	ds_write_b64 v219, v[54:55] offset:2048
	v_fma_f32 v58, v234, v58, v46
	v_fma_f32 v59, v235, v59, v47
	v_fma_f32 v60, v236, v60, v48
	v_fma_f32 v61, v237, v61, v49
	v_cvt_pk_bf16_f32 v58, v58, v59
	v_cvt_pk_bf16_f32 v59, v60, v61
	ds_write_b64 v220, v[58:59] offset:2048
	v_fma_f32 v34, v238, v34, v50
	v_fma_f32 v35, v239, v35, v51
	v_fma_f32 v36, v240, v36, v52
	v_fma_f32 v37, v241, v37, v53
	v_cvt_pk_bf16_f32 v34, v34, v35
	v_cvt_pk_bf16_f32 v35, v36, v37
	ds_write_b64 v221, v[34:35] offset:2048
	v_fma_f32 v30, v226, v30, v38
	v_fma_f32 v31, v227, v31, v39
	v_fma_f32 v32, v228, v32, v40
	v_fma_f32 v33, v229, v33, v41
	v_cvt_pk_bf16_f32 v30, v30, v31
	v_cvt_pk_bf16_f32 v31, v32, v33
	ds_write_b64 v218, v[30:31] offset:4096
	v_fma_f32 v26, v230, v26, v42
	v_fma_f32 v27, v231, v27, v43
	v_fma_f32 v28, v232, v28, v44
	v_fma_f32 v29, v233, v29, v45
	v_cvt_pk_bf16_f32 v26, v26, v27
	v_cvt_pk_bf16_f32 v27, v28, v29
	ds_write_b64 v219, v[26:27] offset:4096
	v_fma_f32 v22, v234, v22, v46
	v_fma_f32 v23, v235, v23, v47
	v_fma_f32 v24, v236, v24, v48
	v_fma_f32 v25, v237, v25, v49
	v_cvt_pk_bf16_f32 v22, v22, v23
	v_cvt_pk_bf16_f32 v23, v24, v25
	ds_write_b64 v220, v[22:23] offset:4096
	v_fma_f32 v18, v238, v18, v50
	v_fma_f32 v19, v239, v19, v51
	v_fma_f32 v20, v240, v20, v52
	v_fma_f32 v21, v241, v21, v53
	v_cvt_pk_bf16_f32 v18, v18, v19
	v_cvt_pk_bf16_f32 v19, v20, v21
	ds_write_b64 v221, v[18:19] offset:4096
	v_fma_f32 v14, v226, v14, v38
	v_fma_f32 v15, v227, v15, v39
	v_fma_f32 v16, v228, v16, v40
	v_fma_f32 v17, v229, v17, v41
	v_cvt_pk_bf16_f32 v14, v14, v15
	v_cvt_pk_bf16_f32 v15, v16, v17
	ds_write_b64 v218, v[14:15] offset:6144
	v_fma_f32 v10, v230, v10, v42
	v_fma_f32 v11, v231, v11, v43
	v_fma_f32 v12, v232, v12, v44
	v_fma_f32 v13, v233, v13, v45
	v_cvt_pk_bf16_f32 v10, v10, v11
	v_cvt_pk_bf16_f32 v11, v12, v13
	ds_write_b64 v219, v[10:11] offset:6144
	v_fma_f32 v6, v234, v6, v46
	v_fma_f32 v7, v235, v7, v47
	v_fma_f32 v8, v236, v8, v48
	v_fma_f32 v9, v237, v9, v49
	v_cvt_pk_bf16_f32 v6, v6, v7
	v_cvt_pk_bf16_f32 v7, v8, v9
	ds_write_b64 v220, v[6:7] offset:6144
	v_fma_f32 v2, v238, v2, v50
	v_fma_f32 v3, v239, v3, v51
	v_fma_f32 v4, v240, v4, v52
	v_fma_f32 v5, v241, v5, v53
	v_cvt_pk_bf16_f32 v2, v2, v3
	v_cvt_pk_bf16_f32 v3, v4, v5
	ds_write_b64 v221, v[2:3] offset:6144
	s_waitcnt lgkmcnt(0)
	ds_read_b128 v[66:69], v249 offset:0
	ds_read_b128 v[74:77], v249 offset:1024
	ds_read_b128 v[78:81], v249 offset:2048
	ds_read_b128 v[82:85], v249 offset:3072
	ds_read_b128 v[90:93], v249 offset:4096
	ds_read_b128 v[94:97], v249 offset:5120
	ds_read_b128 v[108:111], v249 offset:6144
	ds_read_b128 v[172:175], v249 offset:7168
	s_waitcnt lgkmcnt(7)
	global_store_dwordx4 v248, v[66:69], s[44:45] sc1
	s_waitcnt lgkmcnt(6)
	v_add_u32_e32 v251, 0x4000, v248
	global_store_dwordx4 v251, v[74:77], s[44:45] sc1
	s_waitcnt lgkmcnt(5)
	v_add_u32_e32 v251, 0x8000, v248
	global_store_dwordx4 v251, v[78:81], s[44:45] sc1
	s_waitcnt lgkmcnt(4)
	v_add_u32_e32 v251, 0xc000, v248
	global_store_dwordx4 v251, v[82:85], s[44:45] sc1
	s_waitcnt lgkmcnt(3)
	v_add_u32_e32 v251, 0x10000, v248
	global_store_dwordx4 v251, v[90:93], s[44:45] sc1
	s_waitcnt lgkmcnt(2)
	v_add_u32_e32 v251, 0x14000, v248
	global_store_dwordx4 v251, v[94:97], s[44:45] sc1
	s_waitcnt lgkmcnt(1)
	v_add_u32_e32 v251, 0x18000, v248
	global_store_dwordx4 v251, v[108:111], s[44:45] sc1
	s_waitcnt lgkmcnt(0)
	v_add_u32_e32 v251, 0x1c000, v248
	global_store_dwordx4 v251, v[172:175], s[44:45] sc1
	s_waitcnt vmcnt(0)
	s_barrier
	v_readfirstlane_b32 s6, v137
	s_cmp_lt_u32 s6, 64
	s_cbranch_scc0 .Lln1_nodone
	s_mul_hi_i32 s6, s60, 0x2aaaaaab
	s_lshr_b32 s13, s6, 31
	s_ashr_i32 s6, s6, 2
	s_add_i32 s6, s6, s13
	s_mul_i32 s13, s6, 24
	s_sub_i32 s13, s60, s13
	s_lshl_b32 s13, s13, 3
	s_add_i32 s13, s13, s6
	s_lshl_b32 s13, s13, 4
	v_readlane_b32 s14, v255, 40
	s_add_i32 s14, s14, 0x5d0e1000
	v_mov_b32_e32 v247, s13
	v_mov_b32_e32 v248, s14
	v_mov_b32_e32 v249, s14
	v_mov_b32_e32 v250, s14
	v_mov_b32_e32 v251, s14
	s_add_u32 s36, s94, 0xcbc8000
	s_addc_u32 s37, s95, 0
	s_mov_b64 exec, 1
	global_store_dwordx4 v247, v[248:251], s[36:37] sc1
	s_mov_b64 exec, -1
.Lln1_nodone:
	v_readlane_b32 s78, v255, 33
	v_readlane_b32 s79, v255, 34
	s_barrier
	s_load_dword s6, s[78:79], 0x0
	s_mov_b64 s[76:77], 0x7b4c180
	s_mov_b64 s[68:69], 0x7b54180
	s_mov_b64 s[74:75], 0x68800
	s_waitcnt lgkmcnt(0)
	s_add_i32 s60, s6, s60
	s_cmpk_gt_i32 s60, 0xbf
	s_cbranch_scc0 .LBB0_93

.LBB0_396:
	s_andn2_b64 vcc, exec, s[0:1]
	s_cbranch_vccnz .LBB0_405
	v_readlane_b32 s6, v253, 0
	s_lshl_b32 s6, s6, 9
	v_add_u32_e32 v2, s6, v137
	v_mov_b32_e32 v4, 0
	v_mov_b32_e32 v5, 0
	v_mov_b32_e32 v6, 0
	v_mov_b32_e32 v7, 0
	s_add_u32 s8, s94, 0xc9d8000
	s_addc_u32 s9, s95, 0
	v_cmp_gt_u32_e32 vcc, 0x20000, v2
	v_lshlrev_b32_e32 v2, 4, v2
	s_and_saveexec_b64 s[22:23], vcc
	global_store_dwordx4 v2, v[4:7], s[8:9]
	s_or_b64 exec, exec, s[22:23]
	s_mov_b64 s[0:1], 0
	s_mov_b64 s[8:9], 0
	v_mov_b32_e32 v0, v137
	v_readlane_b32 s6, v254, 45
	v_ashrrev_i32_e32 v2, 6, v0
	s_nop 0
	v_add_u32_e32 v2, s6, v2
	s_movk_i32 s6, 0x1800
	v_cmp_gt_i32_e32 vcc, s6, v2
	s_and_saveexec_b64 s[22:23], vcc
	s_cbranch_execz .LBB0_404
	s_load_dword s6, s[78:79], 0x0
	v_lshlrev_b32_e32 v0, 2, v0
	s_add_u32 s0, s94, s0
	v_and_b32_e32 v8, 0xfc, v0
	s_addc_u32 s1, s95, s1
	v_lshlrev_b32_e32 v0, 2, v8
	s_add_u32 s26, s0, 0x6300000
	v_lshl_add_u64 v[4:5], s[0:1], 0, v[0:1]
	v_lshlrev_b32_e32 v0, 1, v8
	s_addc_u32 s27, s1, 0
	v_or_b32_e32 v10, 0x100, v8
	v_or_b32_e32 v12, 0x200, v8
	s_waitcnt vmcnt(0)
	v_or_b32_e32 v14, 0x300, v8
	s_mov_b64 s[8:9], 0x6348000
	v_lshl_add_u64 v[6:7], s[0:1], 0, v[0:1]
	s_mov_b64 s[0:1], 0x7b48000
	s_waitcnt lgkmcnt(0)
	s_lshl_b32 s6, s6, 3
	v_lshl_add_u64 v[4:5], v[4:5], 0, s[8:9]
	v_lshl_add_u64 v[6:7], v[6:7], 0, s[0:1]
	s_mov_b64 s[34:35], 0
	v_lshlrev_b32_e32 v0, 2, v8
	v_lshlrev_b32_e32 v8, 2, v10
	v_lshlrev_b32_e32 v10, 2, v12
	v_lshlrev_b32_e32 v12, 2, v14
	s_branch .LBB0_400
